# saddr-form LDS-DMA (SGPR base + VGPR offset, no 64-bit VALU address add) in K-loops on top of static priority for waves 0-3
# speedup vs baseline: 1.0030x; 1.0007x over previous
; #define PG8_STAGE(bufoff, gbase, voff) do { _Pragma("unroll") for (int _i = 0; _i < 2; ++_i) \
;         __builtin_amdgcn_global_load_lds((const unsigned*)((const char*)(gbase) + (voff)[_i]), (PG8_LAS unsigned*)(lds + (bufoff) + ldsw + _i * 8192), 16, 0, 0); } while (0)
; #define PG8_LDA(dst, b, h) do { _Pragma("unroll") for (int m = 0; m < 4; ++m) _Pragma("unroll") for (int k = 0; k < 2; ++k) dst[m][k] = *(const PG8_LAS bf16x8*)(lds + PG8_SA(b, h) + aoff + m * 2048 + k * 1024); } while (0)
; #define PG8_LDB(dst, b, h) do { _Pragma("unroll") for (int n = 0; n < 2; ++n) _Pragma("unroll") for (int k = 0; k < 2; ++k) dst[n][k] = *(const PG8_LAS bf16x8*)(lds + PG8_SB(b, h) + boff + n * 2048 + k * 1024); } while (0)
; #define PG8_MMA(ai, bj, At, Bt) do { __builtin_amdgcn_s_setprio(1); _Pragma("unroll") for (int m = 0; m < 4; ++m) _Pragma("unroll") for (int n = 0; n < 2; ++n) _Pragma("unroll") for (int k = 0; k < 2; ++k) \
;         acc[ai][bj][m][n] = __builtin_amdgcn_mfma_f32_16x16x32_bf16(Bt[n][k], At[m][k], acc[ai][bj][m][n], 0, 0, 0); __builtin_amdgcn_s_setprio(0); } while (0)
; #define PG8_WAIT_V(n) asm volatile("s_waitcnt vmcnt(" #n ")" ::: "memory")
; #define PG8_WAIT_L(n) asm volatile("s_waitcnt lgkmcnt(" #n ")" ::: "memory")
; #define PG8_BAR __builtin_amdgcn_s_barrier()
; template <class Epi, class Sched, bool ALIGN_EPI = false, bool SP2 = false>
; __device__ __forceinline__ void gemm_phase(PG8_LAS unsigned char* lds, const Gemm g, const Sched& S, const Epi& E, int wave_s) {
;     ...
;             const char* a1 = cA + (size_t)(t + 1) * kstep;
;             const char* a2 = last ? nA : cA + (size_t)(t + 2) * kstep; const char* b2 = last ? nB : cB + (size_t)(t + 2) * kstep;
;             const char* a3 = a2 + kstep; const char* b3 = b2 + kstep;
;             if (last && has_next) S.a_ready(nxt);
;             if constexpr (SP2) {
;             PG8_LDB(B0, 0, 0); PG8_LDB(B1, 0, 1); PG8_SCHED; PG8_LDA(At, 0, 0); PG8_STAGE(PG8_SA(1, 1), a1 + hstep, voffA);
;             PG8_WAIT_V(8); PG8_WAIT_L(0); PG8_BAR; PG8_MMA(0, 0, At, B0); PG8_MMA(0, 1, At, B1); PG8_BAR; PG8_SCHED;
;             PG8_LDA(At, 0, 1); PG8_STAGE(PG8_SB(0, 0), b2, voffB); PG8_STAGE(PG8_SB(0, 1), b2 + hstep, voffB); PG8_STAGE(PG8_SA(0, 0), a2, voffA);
;             PG8_WAIT_V(8); PG8_WAIT_L(0); PG8_BAR; PG8_MMA(1, 0, At, B0); PG8_MMA(1, 1, At, B1); PG8_BAR; PG8_SCHED;
.LBB0_41:
	ds_read_b128 v[144:147], v158 offset:3072
	ds_read_b128 v[148:151], v158 offset:2048
	ds_read_b128 v[152:155], v158 offset:1024
	ds_read_b128 v[160:163], v158
	ds_read_b128 v[164:167], v157 offset:3072
	ds_read_b128 v[168:171], v157 offset:2048
	ds_read_b128 v[172:175], v157 offset:1024
	ds_read_b128 v[176:179], v157
	s_add_u32 s48, s46, 0xfff00080
	s_addc_u32 s49, s47, -1
	s_cmp_eq_u32 s86, 60
	s_cselect_b32 s51, s31, s49
	s_cselect_b32 s50, s72, s48
	s_cselect_b32 s49, s35, s85
	s_cselect_b32 s48, s73, s84
	s_mov_b32 m0, s74
	s_nop 0
	ds_read_b128 v[180:183], v159
	ds_read_b128 v[184:187], v159 offset:1024
	ds_read_b128 v[188:191], v159 offset:2048
	ds_read_b128 v[192:195], v159 offset:3072
	ds_read_b128 v[196:199], v159 offset:4096
	ds_read_b128 v[200:203], v159 offset:5120
	ds_read_b128 v[204:207], v159 offset:6144
	ds_read_b128 v[208:211], v159 offset:7168
	global_load_lds_dwordx4 v138, s[46:47]
	s_nop 0
	s_mov_b32 m0, s75
	s_nop 0
	global_load_lds_dwordx4 v140, s[46:47]
	s_waitcnt vmcnt(8)
	s_waitcnt lgkmcnt(0)
	s_barrier
	v_mfma_f32_16x16x32_bf16 v[124:127], v[176:179], v[180:183], v[124:127]
	v_mfma_f32_16x16x32_bf16 v[124:127], v[172:175], v[184:187], v[124:127]
	v_mfma_f32_16x16x32_bf16 v[120:123], v[164:167], v[184:187], v[120:123]
	v_mfma_f32_16x16x32_bf16 v[120:123], v[168:171], v[180:183], v[120:123]
	v_mfma_f32_16x16x32_bf16 v[104:107], v[168:171], v[188:191], v[104:107]
	v_mfma_f32_16x16x32_bf16 v[104:107], v[164:167], v[192:195], v[104:107]
	v_mfma_f32_16x16x32_bf16 v[108:111], v[172:175], v[192:195], v[108:111]
	v_mfma_f32_16x16x32_bf16 v[108:111], v[176:179], v[188:191], v[108:111]
	v_mfma_f32_16x16x32_bf16 v[92:95], v[176:179], v[196:199], v[92:95]
	v_mfma_f32_16x16x32_bf16 v[92:95], v[172:175], v[200:203], v[92:95]
	v_mfma_f32_16x16x32_bf16 v[88:91], v[164:167], v[200:203], v[88:91]
	v_mfma_f32_16x16x32_bf16 v[88:91], v[168:171], v[196:199], v[88:91]
	v_mfma_f32_16x16x32_bf16 v[56:59], v[168:171], v[204:207], v[56:59]
	v_mfma_f32_16x16x32_bf16 v[56:59], v[164:167], v[208:211], v[56:59]
	v_mfma_f32_16x16x32_bf16 v[64:67], v[172:175], v[208:211], v[64:67]
	v_mfma_f32_16x16x32_bf16 v[64:67], v[176:179], v[204:207], v[64:67]
	v_mfma_f32_16x16x32_bf16 v[116:119], v[160:163], v[180:183], v[116:119]
	v_mfma_f32_16x16x32_bf16 v[116:119], v[152:155], v[184:187], v[116:119]
	v_mfma_f32_16x16x32_bf16 v[112:115], v[144:147], v[184:187], v[112:115]
	v_mfma_f32_16x16x32_bf16 v[112:115], v[148:151], v[180:183], v[112:115]
	v_mfma_f32_16x16x32_bf16 v[96:99], v[148:151], v[188:191], v[96:99]
	v_mfma_f32_16x16x32_bf16 v[96:99], v[144:147], v[192:195], v[96:99]
	v_mfma_f32_16x16x32_bf16 v[100:103], v[152:155], v[192:195], v[100:103]
	v_mfma_f32_16x16x32_bf16 v[100:103], v[160:163], v[188:191], v[100:103]
	v_mfma_f32_16x16x32_bf16 v[84:87], v[160:163], v[196:199], v[84:87]
	v_mfma_f32_16x16x32_bf16 v[84:87], v[152:155], v[200:203], v[84:87]
	v_mfma_f32_16x16x32_bf16 v[80:83], v[144:147], v[200:203], v[80:83]
	v_mfma_f32_16x16x32_bf16 v[80:83], v[148:151], v[196:199], v[80:83]
	v_mfma_f32_16x16x32_bf16 v[48:51], v[148:151], v[204:207], v[48:51]
	v_mfma_f32_16x16x32_bf16 v[48:51], v[144:147], v[208:211], v[48:51]
	v_mfma_f32_16x16x32_bf16 v[52:55], v[152:155], v[208:211], v[52:55]
	v_mfma_f32_16x16x32_bf16 v[52:55], v[160:163], v[204:207], v[52:55]
	s_barrier
	s_mov_b32 m0, s76
	v_lshl_add_u64 v[212:213], s[48:49], 0, v[132:133]
	s_add_u32 s88, s48, 0x100000
	ds_read_b128 v[180:183], v159 offset:16384
	ds_read_b128 v[184:187], v159 offset:17408
	ds_read_b128 v[188:191], v159 offset:18432
	ds_read_b128 v[192:195], v159 offset:19456
	ds_read_b128 v[196:199], v159 offset:20480
	ds_read_b128 v[200:203], v159 offset:21504
	ds_read_b128 v[204:207], v159 offset:22528
	ds_read_b128 v[208:211], v159 offset:23552
	global_load_lds_dwordx4 v[212:213], off
	v_lshl_add_u64 v[214:215], s[48:49], 0, v[128:129]
	s_mov_b32 m0, s77
	s_addc_u32 s89, s49, 0
	global_load_lds_dwordx4 v[214:215], off
	s_nop 0
	s_mov_b32 m0, s78
	v_lshl_add_u64 v[218:219], s[50:51], 0, v[130:131]
	global_load_lds_dwordx4 v132, s[88:89]
	s_nop 0
	s_mov_b32 m0, s79
	s_nop 0
	global_load_lds_dwordx4 v128, s[88:89]
	v_lshl_add_u64 v[216:217], s[50:51], 0, v[134:135]
	s_mov_b32 m0, s43
	s_nop 0
	global_load_lds_dwordx4 v[216:217], off
	s_mov_b32 m0, s57
	s_nop 0
	global_load_lds_dwordx4 v[218:219], off
	s_waitcnt vmcnt(8)
	s_waitcnt lgkmcnt(0)
	s_barrier
	v_mfma_f32_16x16x32_bf16 v[76:79], v[176:179], v[180:183], v[76:79]
	v_mfma_f32_16x16x32_bf16 v[76:79], v[172:175], v[184:187], v[76:79]
	v_mfma_f32_16x16x32_bf16 v[72:75], v[164:167], v[184:187], v[72:75]
	v_mfma_f32_16x16x32_bf16 v[72:75], v[168:171], v[180:183], v[72:75]
	v_mfma_f32_16x16x32_bf16 v[40:43], v[168:171], v[188:191], v[40:43]
	v_mfma_f32_16x16x32_bf16 v[40:43], v[164:167], v[192:195], v[40:43]
	v_mfma_f32_16x16x32_bf16 v[44:47], v[172:175], v[192:195], v[44:47]
	v_mfma_f32_16x16x32_bf16 v[44:47], v[176:179], v[188:191], v[44:47]
	v_mfma_f32_16x16x32_bf16 v[28:31], v[176:179], v[196:199], v[28:31]
	v_mfma_f32_16x16x32_bf16 v[28:31], v[172:175], v[200:203], v[28:31]
	v_mfma_f32_16x16x32_bf16 v[24:27], v[164:167], v[200:203], v[24:27]
	v_mfma_f32_16x16x32_bf16 v[24:27], v[168:171], v[196:199], v[24:27]
	v_mfma_f32_16x16x32_bf16 v[8:11], v[168:171], v[204:207], v[8:11]
	v_mfma_f32_16x16x32_bf16 v[8:11], v[164:167], v[208:211], v[8:11]
	v_mfma_f32_16x16x32_bf16 v[12:15], v[172:175], v[208:211], v[12:15]
	v_mfma_f32_16x16x32_bf16 v[12:15], v[176:179], v[204:207], v[12:15]
	v_mfma_f32_16x16x32_bf16 v[68:71], v[160:163], v[180:183], v[68:71]
	v_mfma_f32_16x16x32_bf16 v[68:71], v[152:155], v[184:187], v[68:71]
	v_mfma_f32_16x16x32_bf16 v[60:63], v[144:147], v[184:187], v[60:63]
	v_mfma_f32_16x16x32_bf16 v[60:63], v[148:151], v[180:183], v[60:63]
	v_mfma_f32_16x16x32_bf16 v[32:35], v[148:151], v[188:191], v[32:35]
	v_mfma_f32_16x16x32_bf16 v[32:35], v[144:147], v[192:195], v[32:35]
	v_mfma_f32_16x16x32_bf16 v[36:39], v[152:155], v[192:195], v[36:39]
	v_mfma_f32_16x16x32_bf16 v[36:39], v[160:163], v[188:191], v[36:39]
	v_mfma_f32_16x16x32_bf16 v[20:23], v[160:163], v[196:199], v[20:23]
	v_mfma_f32_16x16x32_bf16 v[20:23], v[152:155], v[200:203], v[20:23]
	v_mfma_f32_16x16x32_bf16 v[16:19], v[144:147], v[200:203], v[16:19]
	v_mfma_f32_16x16x32_bf16 v[16:19], v[148:151], v[196:199], v[16:19]
	v_mfma_f32_16x16x32_bf16 v[0:3], v[148:151], v[204:207], v[0:3]
	v_mfma_f32_16x16x32_bf16 v[0:3], v[144:147], v[208:211], v[0:3]
	v_mfma_f32_16x16x32_bf16 v[4:7], v[152:155], v[208:211], v[4:7]
	v_mfma_f32_16x16x32_bf16 v[4:7], v[160:163], v[204:207], v[4:7]
	s_barrier
; #define PG8_LAS __attribute__((address_space(3)))
; #define PG8_STAGE(bufoff, gbase, voff) do { _Pragma("unroll") for (int _i = 0; _i < 2; ++_i) \
;         __builtin_amdgcn_global_load_lds((const unsigned*)((const char*)(gbase) + (voff)[_i]), (PG8_LAS unsigned*)(lds + (bufoff) + ldsw + _i * 8192), 16, 0, 0); } while (0)
; #define PG8_LDA(dst, b, h) do { _Pragma("unroll") for (int m = 0; m < 4; ++m) _Pragma("unroll") for (int k = 0; k < 2; ++k) dst[m][k] = *(const PG8_LAS bf16x8*)(lds + PG8_SA(b, h) + aoff + m * 2048 + k * 1024); } while (0)
; #define PG8_LDB(dst, b, h) do { _Pragma("unroll") for (int n = 0; n < 2; ++n) _Pragma("unroll") for (int k = 0; k < 2; ++k) dst[n][k] = *(const PG8_LAS bf16x8*)(lds + PG8_SB(b, h) + boff + n * 2048 + k * 1024); } while (0)
; #define PG8_WAIT_V(n) asm volatile("s_waitcnt vmcnt(" #n ")" ::: "memory")
; #define PG8_WAIT_L(n) asm volatile("s_waitcnt lgkmcnt(" #n ")" ::: "memory")
; #define PG8_BAR __builtin_amdgcn_s_barrier()
; #define PG8_SCHED __builtin_amdgcn_sched_barrier(0)
; template <class Epi, class Sched, bool ALIGN_EPI = false, bool SP2 = false>
; __device__ __forceinline__ void gemm_phase(PG8_LAS unsigned char* lds, const Gemm g, const Sched& S, const Epi& E, int wave_s) {
;     ...
;         for (int t = 0; t < nt; t += 2) {
;             const bool last = (t == nt - 2);
;             if constexpr (Epi::NEED_RS) { if (t == 0 && wid < 4) __builtin_amdgcn_global_load_lds((const unsigned*)(E.rstd + cur.pm * BM + wid * 64 + lane), (PG8_LAS unsigned*)(rsl + wid * 64), 4, 0, 0); }
;             const char* a1 = cA + (size_t)(t + 1) * kstep;
;             const char* a2 = last ? nA : cA + (size_t)(t + 2) * kstep; const char* b2 = last ? nB : cB + (size_t)(t + 2) * kstep;
;             const char* a3 = a2 + kstep; const char* b3 = b2 + kstep;
;     ...
;             PG8_LDB(B0, 1, 0); PG8_LDB(B1, 1, 1); PG8_SCHED; PG8_LDA(At, 1, 0); PG8_STAGE(PG8_SA(0, 1), a2 + hstep, voffA);
;             PG8_WAIT_V(8); PG8_WAIT_L(0); PG8_BAR; PG8_MMA(0, 0, At, B0); PG8_MMA(0, 1, At, B1); PG8_BAR; PG8_SCHED;
;             PG8_LDA(At, 1, 1); PG8_STAGE(PG8_SB(1, 0), b3, voffB); PG8_STAGE(PG8_SB(1, 1), b3 + hstep, voffB); PG8_STAGE(PG8_SA(1, 0), a3, voffA);
;             PG8_WAIT_V(8); PG8_WAIT_L(0); PG8_BAR; PG8_MMA(1, 0, At, B0); PG8_MMA(1, 1, At, B1); PG8_BAR; PG8_SCHED;
	ds_read_b128 v[144:147], v142
	ds_read_b128 v[148:151], v142 offset:1024
	ds_read_b128 v[152:155], v142 offset:2048
	ds_read_b128 v[160:163], v142 offset:3072
	ds_read_b128 v[164:167], v143
	ds_read_b128 v[168:171], v143 offset:1024
	ds_read_b128 v[172:175], v143 offset:2048
	ds_read_b128 v[176:179], v143 offset:3072
	s_add_u32 s50, s50, 0x100000
	s_addc_u32 s51, s51, 0
	s_mov_b32 m0, s58
	s_nop 0
	ds_read_b128 v[180:183], v159 offset:32768
	ds_read_b128 v[184:187], v159 offset:33792
	ds_read_b128 v[188:191], v159 offset:34816
	ds_read_b128 v[192:195], v159 offset:35840
	ds_read_b128 v[196:199], v159 offset:36864
	ds_read_b128 v[200:203], v159 offset:37888
	ds_read_b128 v[204:207], v159 offset:38912
	ds_read_b128 v[208:211], v159 offset:39936
	global_load_lds_dwordx4 v134, s[50:51]
	v_lshl_add_u64 v[220:221], s[50:51], 0, v[130:131]
	s_mov_b32 m0, s59
	s_nop 0
	global_load_lds_dwordx4 v[220:221], off
	s_waitcnt vmcnt(8)
	s_waitcnt lgkmcnt(0)
	s_barrier
	v_mfma_f32_16x16x32_bf16 v[124:127], v[144:147], v[180:183], v[124:127]
	v_mfma_f32_16x16x32_bf16 v[124:127], v[148:151], v[184:187], v[124:127]
	v_mfma_f32_16x16x32_bf16 v[120:123], v[160:163], v[184:187], v[120:123]
	v_mfma_f32_16x16x32_bf16 v[120:123], v[152:155], v[180:183], v[120:123]
	v_mfma_f32_16x16x32_bf16 v[104:107], v[152:155], v[188:191], v[104:107]
	v_mfma_f32_16x16x32_bf16 v[104:107], v[160:163], v[192:195], v[104:107]
	v_mfma_f32_16x16x32_bf16 v[108:111], v[148:151], v[192:195], v[108:111]
	v_mfma_f32_16x16x32_bf16 v[108:111], v[144:147], v[188:191], v[108:111]
	v_mfma_f32_16x16x32_bf16 v[92:95], v[144:147], v[196:199], v[92:95]
	v_mfma_f32_16x16x32_bf16 v[92:95], v[148:151], v[200:203], v[92:95]
	v_mfma_f32_16x16x32_bf16 v[88:91], v[160:163], v[200:203], v[88:91]
	v_mfma_f32_16x16x32_bf16 v[88:91], v[152:155], v[196:199], v[88:91]
	v_mfma_f32_16x16x32_bf16 v[56:59], v[152:155], v[204:207], v[56:59]
	v_mfma_f32_16x16x32_bf16 v[56:59], v[160:163], v[208:211], v[56:59]
	v_mfma_f32_16x16x32_bf16 v[64:67], v[148:151], v[208:211], v[64:67]
	v_mfma_f32_16x16x32_bf16 v[64:67], v[144:147], v[204:207], v[64:67]
	v_mfma_f32_16x16x32_bf16 v[116:119], v[164:167], v[180:183], v[116:119]
	v_mfma_f32_16x16x32_bf16 v[116:119], v[168:171], v[184:187], v[116:119]
	v_mfma_f32_16x16x32_bf16 v[112:115], v[176:179], v[184:187], v[112:115]
	v_mfma_f32_16x16x32_bf16 v[112:115], v[172:175], v[180:183], v[112:115]
	v_mfma_f32_16x16x32_bf16 v[96:99], v[172:175], v[188:191], v[96:99]
	v_mfma_f32_16x16x32_bf16 v[96:99], v[176:179], v[192:195], v[96:99]
	v_mfma_f32_16x16x32_bf16 v[100:103], v[168:171], v[192:195], v[100:103]
	v_mfma_f32_16x16x32_bf16 v[100:103], v[164:167], v[188:191], v[100:103]
	v_mfma_f32_16x16x32_bf16 v[84:87], v[164:167], v[196:199], v[84:87]
	v_mfma_f32_16x16x32_bf16 v[84:87], v[168:171], v[200:203], v[84:87]
	v_mfma_f32_16x16x32_bf16 v[80:83], v[176:179], v[200:203], v[80:83]
	v_mfma_f32_16x16x32_bf16 v[80:83], v[172:175], v[196:199], v[80:83]
	v_mfma_f32_16x16x32_bf16 v[48:51], v[172:175], v[204:207], v[48:51]
	v_mfma_f32_16x16x32_bf16 v[48:51], v[176:179], v[208:211], v[48:51]
	v_mfma_f32_16x16x32_bf16 v[52:55], v[168:171], v[208:211], v[52:55]
	v_mfma_f32_16x16x32_bf16 v[52:55], v[164:167], v[204:207], v[52:55]
	s_barrier
	s_mov_b32 m0, s80
	v_lshl_add_u64 v[212:213], v[212:213], 0, s[10:11]
	s_add_u32 s48, s48, 0x100080
	ds_read_b128 v[180:183], v159 offset:49152
	ds_read_b128 v[184:187], v159 offset:50176
	ds_read_b128 v[188:191], v159 offset:51200
	ds_read_b128 v[192:195], v159 offset:52224
	ds_read_b128 v[196:199], v159 offset:53248
	ds_read_b128 v[200:203], v159 offset:54272
	ds_read_b128 v[204:207], v159 offset:55296
	ds_read_b128 v[208:211], v159 offset:56320
	global_load_lds_dwordx4 v[212:213], off
	v_lshl_add_u64 v[212:213], v[214:215], 0, s[10:11]
	s_mov_b32 m0, s81
	s_addc_u32 s49, s49, 0
	global_load_lds_dwordx4 v[212:213], off
	s_nop 0
	s_mov_b32 m0, s82
	s_nop 0
	global_load_lds_dwordx4 v132, s[48:49]
	s_nop 0
	s_mov_b32 m0, s83
	s_nop 0
	global_load_lds_dwordx4 v128, s[48:49]
	v_lshl_add_u64 v[212:213], v[216:217], 0, s[10:11]
	s_mov_b32 m0, s64
	s_nop 0
	global_load_lds_dwordx4 v[212:213], off
	v_lshl_add_u64 v[212:213], v[218:219], 0, s[10:11]
	s_mov_b32 m0, s65
	s_nop 0
	global_load_lds_dwordx4 v[212:213], off
	s_waitcnt vmcnt(8)
	s_waitcnt lgkmcnt(0)
	s_barrier
	v_mfma_f32_16x16x32_bf16 v[76:79], v[144:147], v[180:183], v[76:79]
	v_mfma_f32_16x16x32_bf16 v[76:79], v[148:151], v[184:187], v[76:79]
	v_mfma_f32_16x16x32_bf16 v[72:75], v[160:163], v[184:187], v[72:75]
	v_mfma_f32_16x16x32_bf16 v[72:75], v[152:155], v[180:183], v[72:75]
	v_mfma_f32_16x16x32_bf16 v[40:43], v[152:155], v[188:191], v[40:43]
	v_mfma_f32_16x16x32_bf16 v[40:43], v[160:163], v[192:195], v[40:43]
	v_mfma_f32_16x16x32_bf16 v[44:47], v[148:151], v[192:195], v[44:47]
	v_mfma_f32_16x16x32_bf16 v[44:47], v[144:147], v[188:191], v[44:47]
	v_mfma_f32_16x16x32_bf16 v[28:31], v[144:147], v[196:199], v[28:31]
	v_mfma_f32_16x16x32_bf16 v[28:31], v[148:151], v[200:203], v[28:31]
	v_mfma_f32_16x16x32_bf16 v[24:27], v[160:163], v[200:203], v[24:27]
	v_mfma_f32_16x16x32_bf16 v[24:27], v[152:155], v[196:199], v[24:27]
	v_mfma_f32_16x16x32_bf16 v[8:11], v[152:155], v[204:207], v[8:11]
	v_mfma_f32_16x16x32_bf16 v[8:11], v[160:163], v[208:211], v[8:11]
	v_mfma_f32_16x16x32_bf16 v[12:15], v[148:151], v[208:211], v[12:15]
	v_mfma_f32_16x16x32_bf16 v[12:15], v[144:147], v[204:207], v[12:15]
	v_mfma_f32_16x16x32_bf16 v[68:71], v[164:167], v[180:183], v[68:71]
	v_mfma_f32_16x16x32_bf16 v[68:71], v[168:171], v[184:187], v[68:71]
	v_mfma_f32_16x16x32_bf16 v[60:63], v[176:179], v[184:187], v[60:63]
	v_mfma_f32_16x16x32_bf16 v[60:63], v[172:175], v[180:183], v[60:63]
	v_mfma_f32_16x16x32_bf16 v[32:35], v[172:175], v[188:191], v[32:35]
	v_mfma_f32_16x16x32_bf16 v[32:35], v[176:179], v[192:195], v[32:35]
	v_mfma_f32_16x16x32_bf16 v[36:39], v[168:171], v[192:195], v[36:39]
	v_mfma_f32_16x16x32_bf16 v[36:39], v[164:167], v[188:191], v[36:39]
	v_mfma_f32_16x16x32_bf16 v[20:23], v[164:167], v[196:199], v[20:23]
	v_mfma_f32_16x16x32_bf16 v[20:23], v[168:171], v[200:203], v[20:23]
	v_mfma_f32_16x16x32_bf16 v[16:19], v[176:179], v[200:203], v[16:19]
	v_mfma_f32_16x16x32_bf16 v[16:19], v[172:175], v[196:199], v[16:19]
	v_mfma_f32_16x16x32_bf16 v[0:3], v[172:175], v[204:207], v[0:3]
	v_mfma_f32_16x16x32_bf16 v[0:3], v[176:179], v[208:211], v[0:3]
	v_mfma_f32_16x16x32_bf16 v[4:7], v[168:171], v[208:211], v[4:7]
	v_mfma_f32_16x16x32_bf16 v[4:7], v[164:167], v[204:207], v[4:7]
	s_barrier
	s_add_i32 s86, s86, 2
	s_add_u32 s46, s46, 0x100
	s_addc_u32 s47, s47, 0
	s_add_u32 s84, s84, 0x100
	s_addc_u32 s85, s85, 0
	s_cmp_gt_u32 s86, 61
	s_cbranch_scc0 .LBB0_41
	s_and_b64 vcc, exec, s[14:15]
	s_cbranch_vccz .LBB0_44
	s_barrier

; #define PG8_STAGE(bufoff, gbase, voff) do { _Pragma("unroll") for (int _i = 0; _i < 2; ++_i) \
;         __builtin_amdgcn_global_load_lds((const unsigned*)((const char*)(gbase) + (voff)[_i]), (PG8_LAS unsigned*)(lds + (bufoff) + ldsw + _i * 8192), 16, 0, 0); } while (0)
; #define PG8_LDA(dst, b, h) do { _Pragma("unroll") for (int m = 0; m < 4; ++m) _Pragma("unroll") for (int k = 0; k < 2; ++k) dst[m][k] = *(const PG8_LAS bf16x8*)(lds + PG8_SA(b, h) + aoff + m * 2048 + k * 1024); } while (0)
; #define PG8_LDB(dst, b, h) do { _Pragma("unroll") for (int n = 0; n < 2; ++n) _Pragma("unroll") for (int k = 0; k < 2; ++k) dst[n][k] = *(const PG8_LAS bf16x8*)(lds + PG8_SB(b, h) + boff + n * 2048 + k * 1024); } while (0)
; #define PG8_MMA(ai, bj, At, Bt) do { __builtin_amdgcn_s_setprio(1); _Pragma("unroll") for (int m = 0; m < 4; ++m) _Pragma("unroll") for (int n = 0; n < 2; ++n) _Pragma("unroll") for (int k = 0; k < 2; ++k) \
;         acc[ai][bj][m][n] = __builtin_amdgcn_mfma_f32_16x16x32_bf16(Bt[n][k], At[m][k], acc[ai][bj][m][n], 0, 0, 0); __builtin_amdgcn_s_setprio(0); } while (0)
; #define PG8_WAIT_V(n) asm volatile("s_waitcnt vmcnt(" #n ")" ::: "memory")
; #define PG8_WAIT_L(n) asm volatile("s_waitcnt lgkmcnt(" #n ")" ::: "memory")
; #define PG8_BAR __builtin_amdgcn_s_barrier()
; template <class Epi, class Sched, bool ALIGN_EPI = false, bool SP2 = false>
; __device__ __forceinline__ void gemm_phase(PG8_LAS unsigned char* lds, const Gemm g, const Sched& S, const Epi& E, int wave_s) {
;     ...
;             const char* a1 = cA + (size_t)(t + 1) * kstep;
;             const char* a2 = last ? nA : cA + (size_t)(t + 2) * kstep; const char* b2 = last ? nB : cB + (size_t)(t + 2) * kstep;
;             const char* a3 = a2 + kstep; const char* b3 = b2 + kstep;
;             if (last && has_next) S.a_ready(nxt);
;             if constexpr (SP2) {
;             PG8_LDB(B0, 0, 0); PG8_LDB(B1, 0, 1); PG8_SCHED; PG8_LDA(At, 0, 0); PG8_STAGE(PG8_SA(1, 1), a1 + hstep, voffA);
;             PG8_WAIT_V(8); PG8_WAIT_L(0); PG8_BAR; PG8_MMA(0, 0, At, B0); PG8_MMA(0, 1, At, B1); PG8_BAR; PG8_SCHED;
;             PG8_LDA(At, 0, 1); PG8_STAGE(PG8_SB(0, 0), b2, voffB); PG8_STAGE(PG8_SB(0, 1), b2 + hstep, voffB); PG8_STAGE(PG8_SA(0, 0), a2, voffA);
;             PG8_WAIT_V(8); PG8_WAIT_L(0); PG8_BAR; PG8_MMA(1, 0, At, B0); PG8_MMA(1, 1, At, B1); PG8_BAR; PG8_SCHED;
.LBB0_1200:
	ds_read_b128 v[128:131], v211
	ds_read_b128 v[132:135], v211 offset:1024
	ds_read_b128 v[136:139], v211 offset:2048
	ds_read_b128 v[140:143], v211 offset:3072
	ds_read_b128 v[144:147], v212
	ds_read_b128 v[148:151], v212 offset:1024
	ds_read_b128 v[152:155], v212 offset:2048
	ds_read_b128 v[156:159], v212 offset:3072
	s_add_u32 s45, s50, 0xfff00080
	s_addc_u32 s52, s51, -1
	s_cmp_eq_u32 s85, s43
	s_cselect_b32 s55, s47, s52
	s_cselect_b32 s54, s46, s45
	s_cselect_b32 s53, s49, s41
	s_cselect_b32 s52, s48, s7
	s_nop 0
	s_add_i32 m0, s9, 0xc000
	ds_read_b128 v[160:163], v213
	ds_read_b128 v[164:167], v213 offset:1024
	ds_read_b128 v[168:171], v213 offset:2048
	ds_read_b128 v[172:175], v213 offset:3072
	ds_read_b128 v[176:179], v213 offset:4096
	ds_read_b128 v[180:183], v213 offset:5120
	ds_read_b128 v[196:199], v213 offset:6144
	ds_read_b128 v[200:203], v213 offset:7168
	global_load_lds_dwordx4 v192, s[50:51]
	s_nop 0
	s_add_i32 m0, s9, 0xe000
	s_nop 0
	global_load_lds_dwordx4 v194, s[50:51]
	s_waitcnt vmcnt(8)
	s_waitcnt lgkmcnt(0)
	s_barrier
	v_mfma_f32_16x16x32_bf16 v[124:127], v[128:131], v[160:163], v[124:127]
	v_mfma_f32_16x16x32_bf16 v[124:127], v[132:135], v[164:167], v[124:127]
	v_mfma_f32_16x16x32_bf16 v[120:123], v[140:143], v[164:167], v[120:123]
	v_mfma_f32_16x16x32_bf16 v[120:123], v[136:139], v[160:163], v[120:123]
	v_mfma_f32_16x16x32_bf16 v[104:107], v[136:139], v[168:171], v[104:107]
	v_mfma_f32_16x16x32_bf16 v[104:107], v[140:143], v[172:175], v[104:107]
	v_mfma_f32_16x16x32_bf16 v[108:111], v[132:135], v[172:175], v[108:111]
	v_mfma_f32_16x16x32_bf16 v[108:111], v[128:131], v[168:171], v[108:111]
	v_mfma_f32_16x16x32_bf16 v[92:95], v[128:131], v[176:179], v[92:95]
	v_mfma_f32_16x16x32_bf16 v[92:95], v[132:135], v[180:183], v[92:95]
	v_mfma_f32_16x16x32_bf16 v[88:91], v[140:143], v[180:183], v[88:91]
	v_mfma_f32_16x16x32_bf16 v[88:91], v[136:139], v[176:179], v[88:91]
	v_mfma_f32_16x16x32_bf16 v[72:75], v[136:139], v[196:199], v[72:75]
	v_mfma_f32_16x16x32_bf16 v[72:75], v[140:143], v[200:203], v[72:75]
	v_mfma_f32_16x16x32_bf16 v[76:79], v[132:135], v[200:203], v[76:79]
	v_mfma_f32_16x16x32_bf16 v[76:79], v[128:131], v[196:199], v[76:79]
	v_mfma_f32_16x16x32_bf16 v[116:119], v[144:147], v[160:163], v[116:119]
	v_mfma_f32_16x16x32_bf16 v[116:119], v[148:151], v[164:167], v[116:119]
	v_mfma_f32_16x16x32_bf16 v[112:115], v[156:159], v[164:167], v[112:115]
	v_mfma_f32_16x16x32_bf16 v[112:115], v[152:155], v[160:163], v[112:115]
	v_mfma_f32_16x16x32_bf16 v[96:99], v[152:155], v[168:171], v[96:99]
	v_mfma_f32_16x16x32_bf16 v[96:99], v[156:159], v[172:175], v[96:99]
	v_mfma_f32_16x16x32_bf16 v[100:103], v[148:151], v[172:175], v[100:103]
	v_mfma_f32_16x16x32_bf16 v[100:103], v[144:147], v[168:171], v[100:103]
	v_mfma_f32_16x16x32_bf16 v[84:87], v[144:147], v[176:179], v[84:87]
	v_mfma_f32_16x16x32_bf16 v[84:87], v[148:151], v[180:183], v[84:87]
	v_mfma_f32_16x16x32_bf16 v[80:83], v[156:159], v[180:183], v[80:83]
	v_mfma_f32_16x16x32_bf16 v[80:83], v[152:155], v[176:179], v[80:83]
	v_mfma_f32_16x16x32_bf16 v[64:67], v[152:155], v[196:199], v[64:67]
	v_mfma_f32_16x16x32_bf16 v[64:67], v[156:159], v[200:203], v[64:67]
	v_mfma_f32_16x16x32_bf16 v[68:71], v[148:151], v[200:203], v[68:71]
	v_mfma_f32_16x16x32_bf16 v[68:71], v[144:147], v[196:199], v[68:71]
	s_barrier
	s_add_i32 s45, s75, s60
	v_lshl_add_u64 v[204:205], s[52:53], 0, v[186:187]
	s_mov_b32 m0, s45
	ds_read_b128 v[160:163], v213 offset:16384
	ds_read_b128 v[164:167], v213 offset:17408
	ds_read_b128 v[168:171], v213 offset:18432
	ds_read_b128 v[172:175], v213 offset:19456
	ds_read_b128 v[176:179], v213 offset:20480
	ds_read_b128 v[180:183], v213 offset:21504
	ds_read_b128 v[196:199], v213 offset:22528
	ds_read_b128 v[200:203], v213 offset:23552
	global_load_lds_dwordx4 v[204:205], off
	s_add_i32 m0, s45, 0x2000
	s_add_u32 s86, s52, 0x100000
	v_lshl_add_u64 v[206:207], s[52:53], 0, v[190:191]
	s_addc_u32 s87, s53, 0
	s_add_i32 s45, s76, s60
	global_load_lds_dwordx4 v[206:207], off
	s_nop 0
	s_mov_b32 m0, s45
	v_lshl_add_u64 v[216:217], s[54:55], 0, v[188:189]
	global_load_lds_dwordx4 v186, s[86:87]
	s_nop 0
	s_add_i32 m0, s45, 0x2000
	s_nop 0
	global_load_lds_dwordx4 v190, s[86:87]
	v_lshl_add_u64 v[208:209], s[54:55], 0, v[184:185]
	s_mov_b32 m0, s9
	s_nop 0
	global_load_lds_dwordx4 v[208:209], off
	s_mov_b32 m0, s61
	s_nop 0
	global_load_lds_dwordx4 v[216:217], off
	s_waitcnt vmcnt(8)
	s_waitcnt lgkmcnt(0)
	s_barrier
	v_mfma_f32_16x16x32_bf16 v[60:63], v[128:131], v[160:163], v[60:63]
	v_mfma_f32_16x16x32_bf16 v[60:63], v[132:135], v[164:167], v[60:63]
	v_mfma_f32_16x16x32_bf16 v[56:59], v[140:143], v[164:167], v[56:59]
	v_mfma_f32_16x16x32_bf16 v[56:59], v[136:139], v[160:163], v[56:59]
	v_mfma_f32_16x16x32_bf16 v[40:43], v[136:139], v[168:171], v[40:43]
	v_mfma_f32_16x16x32_bf16 v[40:43], v[140:143], v[172:175], v[40:43]
	v_mfma_f32_16x16x32_bf16 v[44:47], v[132:135], v[172:175], v[44:47]
	v_mfma_f32_16x16x32_bf16 v[44:47], v[128:131], v[168:171], v[44:47]
	v_mfma_f32_16x16x32_bf16 v[28:31], v[128:131], v[176:179], v[28:31]
	v_mfma_f32_16x16x32_bf16 v[28:31], v[132:135], v[180:183], v[28:31]
	v_mfma_f32_16x16x32_bf16 v[24:27], v[140:143], v[180:183], v[24:27]
	v_mfma_f32_16x16x32_bf16 v[24:27], v[136:139], v[176:179], v[24:27]
	v_mfma_f32_16x16x32_bf16 v[8:11], v[136:139], v[196:199], v[8:11]
	v_mfma_f32_16x16x32_bf16 v[8:11], v[140:143], v[200:203], v[8:11]
	v_mfma_f32_16x16x32_bf16 v[12:15], v[132:135], v[200:203], v[12:15]
	v_mfma_f32_16x16x32_bf16 v[12:15], v[128:131], v[196:199], v[12:15]
	v_mfma_f32_16x16x32_bf16 v[52:55], v[144:147], v[160:163], v[52:55]
	v_mfma_f32_16x16x32_bf16 v[52:55], v[148:151], v[164:167], v[52:55]
	v_mfma_f32_16x16x32_bf16 v[48:51], v[156:159], v[164:167], v[48:51]
	v_mfma_f32_16x16x32_bf16 v[48:51], v[152:155], v[160:163], v[48:51]
	v_mfma_f32_16x16x32_bf16 v[32:35], v[152:155], v[168:171], v[32:35]
	v_mfma_f32_16x16x32_bf16 v[32:35], v[156:159], v[172:175], v[32:35]
	v_mfma_f32_16x16x32_bf16 v[36:39], v[148:151], v[172:175], v[36:39]
	v_mfma_f32_16x16x32_bf16 v[36:39], v[144:147], v[168:171], v[36:39]
	v_mfma_f32_16x16x32_bf16 v[20:23], v[144:147], v[176:179], v[20:23]
	v_mfma_f32_16x16x32_bf16 v[20:23], v[148:151], v[180:183], v[20:23]
	v_mfma_f32_16x16x32_bf16 v[16:19], v[156:159], v[180:183], v[16:19]
	v_mfma_f32_16x16x32_bf16 v[16:19], v[152:155], v[176:179], v[16:19]
	v_mfma_f32_16x16x32_bf16 v[0:3], v[152:155], v[196:199], v[0:3]
	v_mfma_f32_16x16x32_bf16 v[0:3], v[156:159], v[200:203], v[0:3]
	v_mfma_f32_16x16x32_bf16 v[4:7], v[148:151], v[200:203], v[4:7]
	v_mfma_f32_16x16x32_bf16 v[4:7], v[144:147], v[196:199], v[4:7]
	s_barrier
; #define PG8_LAS __attribute__((address_space(3)))
; #define PG8_STAGE(bufoff, gbase, voff) do { _Pragma("unroll") for (int _i = 0; _i < 2; ++_i) \
;         __builtin_amdgcn_global_load_lds((const unsigned*)((const char*)(gbase) + (voff)[_i]), (PG8_LAS unsigned*)(lds + (bufoff) + ldsw + _i * 8192), 16, 0, 0); } while (0)
; #define PG8_LDA(dst, b, h) do { _Pragma("unroll") for (int m = 0; m < 4; ++m) _Pragma("unroll") for (int k = 0; k < 2; ++k) dst[m][k] = *(const PG8_LAS bf16x8*)(lds + PG8_SA(b, h) + aoff + m * 2048 + k * 1024); } while (0)
; #define PG8_LDB(dst, b, h) do { _Pragma("unroll") for (int n = 0; n < 2; ++n) _Pragma("unroll") for (int k = 0; k < 2; ++k) dst[n][k] = *(const PG8_LAS bf16x8*)(lds + PG8_SB(b, h) + boff + n * 2048 + k * 1024); } while (0)
; #define PG8_WAIT_V(n) asm volatile("s_waitcnt vmcnt(" #n ")" ::: "memory")
; #define PG8_WAIT_L(n) asm volatile("s_waitcnt lgkmcnt(" #n ")" ::: "memory")
; #define PG8_BAR __builtin_amdgcn_s_barrier()
; #define PG8_SCHED __builtin_amdgcn_sched_barrier(0)
; template <class Epi, class Sched, bool ALIGN_EPI = false, bool SP2 = false>
; __device__ __forceinline__ void gemm_phase(PG8_LAS unsigned char* lds, const Gemm g, const Sched& S, const Epi& E, int wave_s) {
;     ...
;         for (int t = 0; t < nt; t += 2) {
;             const bool last = (t == nt - 2);
;             if constexpr (Epi::NEED_RS) { if (t == 0 && wid < 4) __builtin_amdgcn_global_load_lds((const unsigned*)(E.rstd + cur.pm * BM + wid * 64 + lane), (PG8_LAS unsigned*)(rsl + wid * 64), 4, 0, 0); }
;             const char* a1 = cA + (size_t)(t + 1) * kstep;
;             const char* a2 = last ? nA : cA + (size_t)(t + 2) * kstep; const char* b2 = last ? nB : cB + (size_t)(t + 2) * kstep;
;             const char* a3 = a2 + kstep; const char* b3 = b2 + kstep;
;     ...
;             PG8_LDB(B0, 1, 0); PG8_LDB(B1, 1, 1); PG8_SCHED; PG8_LDA(At, 1, 0); PG8_STAGE(PG8_SA(0, 1), a2 + hstep, voffA);
;             PG8_WAIT_V(8); PG8_WAIT_L(0); PG8_BAR; PG8_MMA(0, 0, At, B0); PG8_MMA(0, 1, At, B1); PG8_BAR; PG8_SCHED;
;             PG8_LDA(At, 1, 1); PG8_STAGE(PG8_SB(1, 0), b3, voffB); PG8_STAGE(PG8_SB(1, 1), b3 + hstep, voffB); PG8_STAGE(PG8_SA(1, 0), a3, voffA);
;             PG8_WAIT_V(8); PG8_WAIT_L(0); PG8_BAR; PG8_MMA(1, 0, At, B0); PG8_MMA(1, 1, At, B1); PG8_BAR; PG8_SCHED;
	s_add_i32 s45, 0, 0x18000
	s_add_i32 s86, 0, 0x1c000
	v_add_u32_e32 v140, s45, v210
	v_add_u32_e32 v156, s86, v210
	ds_read_b128 v[128:131], v140
	ds_read_b128 v[132:135], v140 offset:1024
	ds_read_b128 v[136:139], v140 offset:2048
	ds_read_b128 v[140:143], v140 offset:3072
	ds_read_b128 v[144:147], v156
	ds_read_b128 v[148:151], v156 offset:1024
	ds_read_b128 v[152:155], v156 offset:2048
	ds_read_b128 v[156:159], v156 offset:3072
	s_add_u32 s54, s54, 0x100000
	s_addc_u32 s55, s55, 0
	s_mov_b32 m0, s62
	s_nop 0
	ds_read_b128 v[160:163], v213 offset:32768
	ds_read_b128 v[164:167], v213 offset:33792
	ds_read_b128 v[168:171], v213 offset:34816
	ds_read_b128 v[172:175], v213 offset:35840
	ds_read_b128 v[176:179], v213 offset:36864
	ds_read_b128 v[180:183], v213 offset:37888
	ds_read_b128 v[196:199], v213 offset:38912
	ds_read_b128 v[200:203], v213 offset:39936
	global_load_lds_dwordx4 v184, s[54:55]
	v_lshl_add_u64 v[218:219], s[54:55], 0, v[188:189]
	s_mov_b32 m0, s63
	s_nop 0
	global_load_lds_dwordx4 v[218:219], off
	s_waitcnt vmcnt(8)
	s_waitcnt lgkmcnt(0)
	s_barrier
	v_mfma_f32_16x16x32_bf16 v[124:127], v[128:131], v[160:163], v[124:127]
	v_mfma_f32_16x16x32_bf16 v[124:127], v[132:135], v[164:167], v[124:127]
	v_mfma_f32_16x16x32_bf16 v[120:123], v[140:143], v[164:167], v[120:123]
	v_mfma_f32_16x16x32_bf16 v[120:123], v[136:139], v[160:163], v[120:123]
	v_mfma_f32_16x16x32_bf16 v[104:107], v[136:139], v[168:171], v[104:107]
	v_mfma_f32_16x16x32_bf16 v[104:107], v[140:143], v[172:175], v[104:107]
	v_mfma_f32_16x16x32_bf16 v[108:111], v[132:135], v[172:175], v[108:111]
	v_mfma_f32_16x16x32_bf16 v[108:111], v[128:131], v[168:171], v[108:111]
	v_mfma_f32_16x16x32_bf16 v[92:95], v[128:131], v[176:179], v[92:95]
	v_mfma_f32_16x16x32_bf16 v[92:95], v[132:135], v[180:183], v[92:95]
	v_mfma_f32_16x16x32_bf16 v[88:91], v[140:143], v[180:183], v[88:91]
	v_mfma_f32_16x16x32_bf16 v[88:91], v[136:139], v[176:179], v[88:91]
	v_mfma_f32_16x16x32_bf16 v[72:75], v[136:139], v[196:199], v[72:75]
	v_mfma_f32_16x16x32_bf16 v[72:75], v[140:143], v[200:203], v[72:75]
	v_mfma_f32_16x16x32_bf16 v[76:79], v[132:135], v[200:203], v[76:79]
	v_mfma_f32_16x16x32_bf16 v[76:79], v[128:131], v[196:199], v[76:79]
	v_mfma_f32_16x16x32_bf16 v[116:119], v[144:147], v[160:163], v[116:119]
	v_mfma_f32_16x16x32_bf16 v[116:119], v[148:151], v[164:167], v[116:119]
	v_mfma_f32_16x16x32_bf16 v[112:115], v[156:159], v[164:167], v[112:115]
	v_mfma_f32_16x16x32_bf16 v[112:115], v[152:155], v[160:163], v[112:115]
	v_mfma_f32_16x16x32_bf16 v[96:99], v[152:155], v[168:171], v[96:99]
	v_mfma_f32_16x16x32_bf16 v[96:99], v[156:159], v[172:175], v[96:99]
	v_mfma_f32_16x16x32_bf16 v[100:103], v[148:151], v[172:175], v[100:103]
	v_mfma_f32_16x16x32_bf16 v[100:103], v[144:147], v[168:171], v[100:103]
	v_mfma_f32_16x16x32_bf16 v[84:87], v[144:147], v[176:179], v[84:87]
	v_mfma_f32_16x16x32_bf16 v[84:87], v[148:151], v[180:183], v[84:87]
	v_mfma_f32_16x16x32_bf16 v[80:83], v[156:159], v[180:183], v[80:83]
	v_mfma_f32_16x16x32_bf16 v[80:83], v[152:155], v[176:179], v[80:83]
	v_mfma_f32_16x16x32_bf16 v[64:67], v[152:155], v[196:199], v[64:67]
	v_mfma_f32_16x16x32_bf16 v[64:67], v[156:159], v[200:203], v[64:67]
	v_mfma_f32_16x16x32_bf16 v[68:71], v[148:151], v[200:203], v[68:71]
	v_mfma_f32_16x16x32_bf16 v[68:71], v[144:147], v[196:199], v[68:71]
	s_barrier
	s_add_i32 s45, s45, s60
	v_lshl_add_u64 v[204:205], v[204:205], 0, s[18:19]
	s_mov_b32 m0, s45
	ds_read_b128 v[160:163], v213 offset:49152
	ds_read_b128 v[164:167], v213 offset:50176
	ds_read_b128 v[168:171], v213 offset:51200
	ds_read_b128 v[172:175], v213 offset:52224
	ds_read_b128 v[176:179], v213 offset:53248
	ds_read_b128 v[180:183], v213 offset:54272
	ds_read_b128 v[196:199], v213 offset:55296
	ds_read_b128 v[200:203], v213 offset:56320
	global_load_lds_dwordx4 v[204:205], off
	s_add_i32 m0, s45, 0x2000
	s_add_u32 s52, s52, 0x100080
	v_lshl_add_u64 v[204:205], v[206:207], 0, s[18:19]
	s_addc_u32 s53, s53, 0
	s_add_i32 s45, s86, s60
	global_load_lds_dwordx4 v[204:205], off
	s_nop 0
	s_mov_b32 m0, s45
	s_nop 0
	global_load_lds_dwordx4 v186, s[52:53]
	s_nop 0
	s_add_i32 m0, s45, 0x2000
	s_nop 0
	global_load_lds_dwordx4 v190, s[52:53]
	v_lshl_add_u64 v[204:205], v[208:209], 0, s[18:19]
	s_mov_b32 m0, s70
	s_nop 0
	global_load_lds_dwordx4 v[204:205], off
	v_lshl_add_u64 v[204:205], v[216:217], 0, s[18:19]
	s_mov_b32 m0, s71
	s_nop 0
	global_load_lds_dwordx4 v[204:205], off
	s_waitcnt vmcnt(8)
	s_waitcnt lgkmcnt(0)
	s_barrier
	v_mfma_f32_16x16x32_bf16 v[60:63], v[128:131], v[160:163], v[60:63]
	v_mfma_f32_16x16x32_bf16 v[60:63], v[132:135], v[164:167], v[60:63]
	v_mfma_f32_16x16x32_bf16 v[56:59], v[140:143], v[164:167], v[56:59]
	v_mfma_f32_16x16x32_bf16 v[56:59], v[136:139], v[160:163], v[56:59]
	v_mfma_f32_16x16x32_bf16 v[40:43], v[136:139], v[168:171], v[40:43]
	v_mfma_f32_16x16x32_bf16 v[40:43], v[140:143], v[172:175], v[40:43]
	v_mfma_f32_16x16x32_bf16 v[44:47], v[132:135], v[172:175], v[44:47]
	v_mfma_f32_16x16x32_bf16 v[44:47], v[128:131], v[168:171], v[44:47]
	v_mfma_f32_16x16x32_bf16 v[28:31], v[128:131], v[176:179], v[28:31]
	v_mfma_f32_16x16x32_bf16 v[28:31], v[132:135], v[180:183], v[28:31]
	v_mfma_f32_16x16x32_bf16 v[24:27], v[140:143], v[180:183], v[24:27]
	v_mfma_f32_16x16x32_bf16 v[24:27], v[136:139], v[176:179], v[24:27]
	v_mfma_f32_16x16x32_bf16 v[8:11], v[136:139], v[196:199], v[8:11]
	v_mfma_f32_16x16x32_bf16 v[8:11], v[140:143], v[200:203], v[8:11]
	v_mfma_f32_16x16x32_bf16 v[12:15], v[132:135], v[200:203], v[12:15]
	v_mfma_f32_16x16x32_bf16 v[12:15], v[128:131], v[196:199], v[12:15]
	v_mfma_f32_16x16x32_bf16 v[52:55], v[144:147], v[160:163], v[52:55]
	v_mfma_f32_16x16x32_bf16 v[52:55], v[148:151], v[164:167], v[52:55]
	v_mfma_f32_16x16x32_bf16 v[48:51], v[156:159], v[164:167], v[48:51]
	v_mfma_f32_16x16x32_bf16 v[48:51], v[152:155], v[160:163], v[48:51]
	v_mfma_f32_16x16x32_bf16 v[32:35], v[152:155], v[168:171], v[32:35]
	v_mfma_f32_16x16x32_bf16 v[32:35], v[156:159], v[172:175], v[32:35]
	v_mfma_f32_16x16x32_bf16 v[36:39], v[148:151], v[172:175], v[36:39]
	v_mfma_f32_16x16x32_bf16 v[36:39], v[144:147], v[168:171], v[36:39]
	v_mfma_f32_16x16x32_bf16 v[20:23], v[144:147], v[176:179], v[20:23]
	v_mfma_f32_16x16x32_bf16 v[20:23], v[148:151], v[180:183], v[20:23]
	v_mfma_f32_16x16x32_bf16 v[16:19], v[156:159], v[180:183], v[16:19]
	v_mfma_f32_16x16x32_bf16 v[16:19], v[152:155], v[176:179], v[16:19]
	v_mfma_f32_16x16x32_bf16 v[0:3], v[152:155], v[196:199], v[0:3]
	v_mfma_f32_16x16x32_bf16 v[0:3], v[156:159], v[200:203], v[0:3]
	v_mfma_f32_16x16x32_bf16 v[4:7], v[148:151], v[200:203], v[4:7]
	v_mfma_f32_16x16x32_bf16 v[4:7], v[144:147], v[196:199], v[4:7]
	s_barrier
	s_add_i32 s45, s43, 2
	s_add_u32 s50, s50, 0x100
	s_addc_u32 s51, s51, 0
	s_add_u32 s7, s7, 0x100
	s_addc_u32 s41, s41, 0
	s_cmp_ge_i32 s43, s85
	s_mov_b32 s43, s45
	s_cbranch_scc0 .LBB0_1200
	s_and_b64 vcc, exec, s[20:21]
	s_cbranch_vccz .LBB0_1203
	s_barrier

; #define PG8_STAGE(bufoff, gbase, voff) do { _Pragma("unroll") for (int _i = 0; _i < 2; ++_i) \
;         __builtin_amdgcn_global_load_lds((const unsigned*)((const char*)(gbase) + (voff)[_i]), (PG8_LAS unsigned*)(lds + (bufoff) + ldsw + _i * 8192), 16, 0, 0); } while (0)
; #define PG8_LDA(dst, b, h) do { _Pragma("unroll") for (int m = 0; m < 4; ++m) _Pragma("unroll") for (int k = 0; k < 2; ++k) dst[m][k] = *(const PG8_LAS bf16x8*)(lds + PG8_SA(b, h) + aoff + m * 2048 + k * 1024); } while (0)
; #define PG8_LDB(dst, b, h) do { _Pragma("unroll") for (int n = 0; n < 2; ++n) _Pragma("unroll") for (int k = 0; k < 2; ++k) dst[n][k] = *(const PG8_LAS bf16x8*)(lds + PG8_SB(b, h) + boff + n * 2048 + k * 1024); } while (0)
; #define PG8_MMA(ai, bj, At, Bt) do { __builtin_amdgcn_s_setprio(1); _Pragma("unroll") for (int m = 0; m < 4; ++m) _Pragma("unroll") for (int n = 0; n < 2; ++n) _Pragma("unroll") for (int k = 0; k < 2; ++k) \
;         acc[ai][bj][m][n] = __builtin_amdgcn_mfma_f32_16x16x32_bf16(Bt[n][k], At[m][k], acc[ai][bj][m][n], 0, 0, 0); __builtin_amdgcn_s_setprio(0); } while (0)
; #define PG8_WAIT_V(n) asm volatile("s_waitcnt vmcnt(" #n ")" ::: "memory")
; #define PG8_WAIT_L(n) asm volatile("s_waitcnt lgkmcnt(" #n ")" ::: "memory")
; #define PG8_BAR __builtin_amdgcn_s_barrier()
; template <class Epi, class Sched, bool ALIGN_EPI = false, bool SP2 = false>
; __device__ __forceinline__ void gemm_phase(PG8_LAS unsigned char* lds, const Gemm g, const Sched& S, const Epi& E, int wave_s) {
;     ...
;             const char* a1 = cA + (size_t)(t + 1) * kstep;
;             const char* a2 = last ? nA : cA + (size_t)(t + 2) * kstep; const char* b2 = last ? nB : cB + (size_t)(t + 2) * kstep;
;             const char* a3 = a2 + kstep; const char* b3 = b2 + kstep;
;             if (last && has_next) S.a_ready(nxt);
;             if constexpr (SP2) {
;             PG8_LDB(B0, 0, 0); PG8_LDB(B1, 0, 1); PG8_SCHED; PG8_LDA(At, 0, 0); PG8_STAGE(PG8_SA(1, 1), a1 + hstep, voffA);
;             PG8_WAIT_V(8); PG8_WAIT_L(0); PG8_BAR; PG8_MMA(0, 0, At, B0); PG8_MMA(0, 1, At, B1); PG8_BAR; PG8_SCHED;
;             PG8_LDA(At, 0, 1); PG8_STAGE(PG8_SB(0, 0), b2, voffB); PG8_STAGE(PG8_SB(0, 1), b2 + hstep, voffB); PG8_STAGE(PG8_SA(0, 0), a2, voffA);
;             PG8_WAIT_V(8); PG8_WAIT_L(0); PG8_BAR; PG8_MMA(1, 0, At, B0); PG8_MMA(1, 1, At, B1); PG8_BAR; PG8_SCHED;
.LBB0_1343:
	ds_read_b128 v[144:147], v150 offset:3072
	ds_read_b128 v[152:155], v150 offset:2048
	ds_read_b128 v[156:159], v150 offset:1024
	ds_read_b128 v[160:163], v150
	ds_read_b128 v[164:167], v149 offset:3072
	ds_read_b128 v[168:171], v149 offset:2048
	ds_read_b128 v[172:175], v149 offset:1024
	ds_read_b128 v[176:179], v149
	s_add_u32 s46, s44, 0xfff00080
	s_addc_u32 s47, s45, -1
	s_cmp_eq_u32 s88, 60
	s_cselect_b32 s49, s29, s47
	s_cselect_b32 s48, s74, s46
	s_cselect_b32 s47, s35, s87
	s_cselect_b32 s46, s75, s86
	s_mov_b32 m0, s76
	s_nop 0
	ds_read_b128 v[180:183], v151
	ds_read_b128 v[184:187], v151 offset:1024
	ds_read_b128 v[188:191], v151 offset:2048
	ds_read_b128 v[192:195], v151 offset:3072
	ds_read_b128 v[196:199], v151 offset:4096
	ds_read_b128 v[200:203], v151 offset:5120
	ds_read_b128 v[204:207], v151 offset:6144
	ds_read_b128 v[208:211], v151 offset:7168
	global_load_lds_dwordx4 v138, s[44:45]
	s_nop 0
	s_mov_b32 m0, s77
	s_nop 0
	global_load_lds_dwordx4 v140, s[44:45]
	s_waitcnt vmcnt(8)
	s_waitcnt lgkmcnt(0)
	s_barrier
	v_mfma_f32_16x16x32_bf16 v[124:127], v[176:179], v[180:183], v[124:127]
	v_mfma_f32_16x16x32_bf16 v[124:127], v[172:175], v[184:187], v[124:127]
	v_mfma_f32_16x16x32_bf16 v[120:123], v[164:167], v[184:187], v[120:123]
	v_mfma_f32_16x16x32_bf16 v[120:123], v[168:171], v[180:183], v[120:123]
	v_mfma_f32_16x16x32_bf16 v[104:107], v[168:171], v[188:191], v[104:107]
	v_mfma_f32_16x16x32_bf16 v[104:107], v[164:167], v[192:195], v[104:107]
	v_mfma_f32_16x16x32_bf16 v[108:111], v[172:175], v[192:195], v[108:111]
	v_mfma_f32_16x16x32_bf16 v[108:111], v[176:179], v[188:191], v[108:111]
	v_mfma_f32_16x16x32_bf16 v[92:95], v[176:179], v[196:199], v[92:95]
	v_mfma_f32_16x16x32_bf16 v[92:95], v[172:175], v[200:203], v[92:95]
	v_mfma_f32_16x16x32_bf16 v[88:91], v[164:167], v[200:203], v[88:91]
	v_mfma_f32_16x16x32_bf16 v[88:91], v[168:171], v[196:199], v[88:91]
	v_mfma_f32_16x16x32_bf16 v[72:75], v[168:171], v[204:207], v[72:75]
	v_mfma_f32_16x16x32_bf16 v[72:75], v[164:167], v[208:211], v[72:75]
	v_mfma_f32_16x16x32_bf16 v[76:79], v[172:175], v[208:211], v[76:79]
	v_mfma_f32_16x16x32_bf16 v[76:79], v[176:179], v[204:207], v[76:79]
	v_mfma_f32_16x16x32_bf16 v[116:119], v[160:163], v[180:183], v[116:119]
	v_mfma_f32_16x16x32_bf16 v[116:119], v[156:159], v[184:187], v[116:119]
	v_mfma_f32_16x16x32_bf16 v[112:115], v[144:147], v[184:187], v[112:115]
	v_mfma_f32_16x16x32_bf16 v[112:115], v[152:155], v[180:183], v[112:115]
	v_mfma_f32_16x16x32_bf16 v[96:99], v[152:155], v[188:191], v[96:99]
	v_mfma_f32_16x16x32_bf16 v[96:99], v[144:147], v[192:195], v[96:99]
	v_mfma_f32_16x16x32_bf16 v[100:103], v[156:159], v[192:195], v[100:103]
	v_mfma_f32_16x16x32_bf16 v[100:103], v[160:163], v[188:191], v[100:103]
	v_mfma_f32_16x16x32_bf16 v[84:87], v[160:163], v[196:199], v[84:87]
	v_mfma_f32_16x16x32_bf16 v[84:87], v[156:159], v[200:203], v[84:87]
	v_mfma_f32_16x16x32_bf16 v[80:83], v[144:147], v[200:203], v[80:83]
	v_mfma_f32_16x16x32_bf16 v[80:83], v[152:155], v[196:199], v[80:83]
	v_mfma_f32_16x16x32_bf16 v[64:67], v[152:155], v[204:207], v[64:67]
	v_mfma_f32_16x16x32_bf16 v[64:67], v[144:147], v[208:211], v[64:67]
	v_mfma_f32_16x16x32_bf16 v[68:71], v[156:159], v[208:211], v[68:71]
	v_mfma_f32_16x16x32_bf16 v[68:71], v[160:163], v[204:207], v[68:71]
	s_barrier
	s_mov_b32 m0, s78
	v_lshl_add_u64 v[212:213], s[46:47], 0, v[132:133]
	s_add_u32 s90, s46, 0x100000
	ds_read_b128 v[180:183], v151 offset:16384
	ds_read_b128 v[184:187], v151 offset:17408
	ds_read_b128 v[188:191], v151 offset:18432
	ds_read_b128 v[192:195], v151 offset:19456
	ds_read_b128 v[196:199], v151 offset:20480
	ds_read_b128 v[200:203], v151 offset:21504
	ds_read_b128 v[204:207], v151 offset:22528
	ds_read_b128 v[208:211], v151 offset:23552
	global_load_lds_dwordx4 v[212:213], off
	v_lshl_add_u64 v[214:215], s[46:47], 0, v[128:129]
	s_mov_b32 m0, s79
	s_addc_u32 s91, s47, 0
	global_load_lds_dwordx4 v[214:215], off
	s_nop 0
	s_mov_b32 m0, s80
	v_lshl_add_u64 v[218:219], s[48:49], 0, v[130:131]
	global_load_lds_dwordx4 v132, s[90:91]
	s_nop 0
	s_mov_b32 m0, s81
	s_nop 0
	global_load_lds_dwordx4 v128, s[90:91]
	v_lshl_add_u64 v[216:217], s[48:49], 0, v[134:135]
	s_mov_b32 m0, s41
	s_nop 0
	global_load_lds_dwordx4 v[216:217], off
	s_mov_b32 m0, s43
	s_nop 0
	global_load_lds_dwordx4 v[218:219], off
	s_waitcnt vmcnt(8)
	s_waitcnt lgkmcnt(0)
	s_barrier
	v_mfma_f32_16x16x32_bf16 v[60:63], v[176:179], v[180:183], v[60:63]
	v_mfma_f32_16x16x32_bf16 v[60:63], v[172:175], v[184:187], v[60:63]
	v_mfma_f32_16x16x32_bf16 v[56:59], v[164:167], v[184:187], v[56:59]
	v_mfma_f32_16x16x32_bf16 v[56:59], v[168:171], v[180:183], v[56:59]
	v_mfma_f32_16x16x32_bf16 v[40:43], v[168:171], v[188:191], v[40:43]
	v_mfma_f32_16x16x32_bf16 v[40:43], v[164:167], v[192:195], v[40:43]
	v_mfma_f32_16x16x32_bf16 v[44:47], v[172:175], v[192:195], v[44:47]
	v_mfma_f32_16x16x32_bf16 v[44:47], v[176:179], v[188:191], v[44:47]
	v_mfma_f32_16x16x32_bf16 v[28:31], v[176:179], v[196:199], v[28:31]
	v_mfma_f32_16x16x32_bf16 v[28:31], v[172:175], v[200:203], v[28:31]
	v_mfma_f32_16x16x32_bf16 v[24:27], v[164:167], v[200:203], v[24:27]
	v_mfma_f32_16x16x32_bf16 v[24:27], v[168:171], v[196:199], v[24:27]
	v_mfma_f32_16x16x32_bf16 v[8:11], v[168:171], v[204:207], v[8:11]
	v_mfma_f32_16x16x32_bf16 v[8:11], v[164:167], v[208:211], v[8:11]
	v_mfma_f32_16x16x32_bf16 v[12:15], v[172:175], v[208:211], v[12:15]
	v_mfma_f32_16x16x32_bf16 v[12:15], v[176:179], v[204:207], v[12:15]
	v_mfma_f32_16x16x32_bf16 v[52:55], v[160:163], v[180:183], v[52:55]
	v_mfma_f32_16x16x32_bf16 v[52:55], v[156:159], v[184:187], v[52:55]
	v_mfma_f32_16x16x32_bf16 v[48:51], v[144:147], v[184:187], v[48:51]
	v_mfma_f32_16x16x32_bf16 v[48:51], v[152:155], v[180:183], v[48:51]
	v_mfma_f32_16x16x32_bf16 v[32:35], v[152:155], v[188:191], v[32:35]
	v_mfma_f32_16x16x32_bf16 v[32:35], v[144:147], v[192:195], v[32:35]
	v_mfma_f32_16x16x32_bf16 v[36:39], v[156:159], v[192:195], v[36:39]
	v_mfma_f32_16x16x32_bf16 v[36:39], v[160:163], v[188:191], v[36:39]
	v_mfma_f32_16x16x32_bf16 v[20:23], v[160:163], v[196:199], v[20:23]
	v_mfma_f32_16x16x32_bf16 v[20:23], v[156:159], v[200:203], v[20:23]
	v_mfma_f32_16x16x32_bf16 v[16:19], v[144:147], v[200:203], v[16:19]
	v_mfma_f32_16x16x32_bf16 v[16:19], v[152:155], v[196:199], v[16:19]
	v_mfma_f32_16x16x32_bf16 v[0:3], v[152:155], v[204:207], v[0:3]
	v_mfma_f32_16x16x32_bf16 v[0:3], v[144:147], v[208:211], v[0:3]
	v_mfma_f32_16x16x32_bf16 v[4:7], v[156:159], v[208:211], v[4:7]
	v_mfma_f32_16x16x32_bf16 v[4:7], v[160:163], v[204:207], v[4:7]
	s_barrier
; #define PG8_LAS __attribute__((address_space(3)))
; #define PG8_STAGE(bufoff, gbase, voff) do { _Pragma("unroll") for (int _i = 0; _i < 2; ++_i) \
;         __builtin_amdgcn_global_load_lds((const unsigned*)((const char*)(gbase) + (voff)[_i]), (PG8_LAS unsigned*)(lds + (bufoff) + ldsw + _i * 8192), 16, 0, 0); } while (0)
; #define PG8_LDA(dst, b, h) do { _Pragma("unroll") for (int m = 0; m < 4; ++m) _Pragma("unroll") for (int k = 0; k < 2; ++k) dst[m][k] = *(const PG8_LAS bf16x8*)(lds + PG8_SA(b, h) + aoff + m * 2048 + k * 1024); } while (0)
; #define PG8_LDB(dst, b, h) do { _Pragma("unroll") for (int n = 0; n < 2; ++n) _Pragma("unroll") for (int k = 0; k < 2; ++k) dst[n][k] = *(const PG8_LAS bf16x8*)(lds + PG8_SB(b, h) + boff + n * 2048 + k * 1024); } while (0)
; #define PG8_WAIT_V(n) asm volatile("s_waitcnt vmcnt(" #n ")" ::: "memory")
; #define PG8_WAIT_L(n) asm volatile("s_waitcnt lgkmcnt(" #n ")" ::: "memory")
; #define PG8_BAR __builtin_amdgcn_s_barrier()
; #define PG8_SCHED __builtin_amdgcn_sched_barrier(0)
; template <class Epi, class Sched, bool ALIGN_EPI = false, bool SP2 = false>
; __device__ __forceinline__ void gemm_phase(PG8_LAS unsigned char* lds, const Gemm g, const Sched& S, const Epi& E, int wave_s) {
;     ...
;         for (int t = 0; t < nt; t += 2) {
;             const bool last = (t == nt - 2);
;             if constexpr (Epi::NEED_RS) { if (t == 0 && wid < 4) __builtin_amdgcn_global_load_lds((const unsigned*)(E.rstd + cur.pm * BM + wid * 64 + lane), (PG8_LAS unsigned*)(rsl + wid * 64), 4, 0, 0); }
;             const char* a1 = cA + (size_t)(t + 1) * kstep;
;             const char* a2 = last ? nA : cA + (size_t)(t + 2) * kstep; const char* b2 = last ? nB : cB + (size_t)(t + 2) * kstep;
;             const char* a3 = a2 + kstep; const char* b3 = b2 + kstep;
;     ...
;             PG8_LDB(B0, 1, 0); PG8_LDB(B1, 1, 1); PG8_SCHED; PG8_LDA(At, 1, 0); PG8_STAGE(PG8_SA(0, 1), a2 + hstep, voffA);
;             PG8_WAIT_V(8); PG8_WAIT_L(0); PG8_BAR; PG8_MMA(0, 0, At, B0); PG8_MMA(0, 1, At, B1); PG8_BAR; PG8_SCHED;
;             PG8_LDA(At, 1, 1); PG8_STAGE(PG8_SB(1, 0), b3, voffB); PG8_STAGE(PG8_SB(1, 1), b3 + hstep, voffB); PG8_STAGE(PG8_SA(1, 0), a3, voffA);
;             PG8_WAIT_V(8); PG8_WAIT_L(0); PG8_BAR; PG8_MMA(1, 0, At, B0); PG8_MMA(1, 1, At, B1); PG8_BAR; PG8_SCHED;
	ds_read_b128 v[144:147], v142
	ds_read_b128 v[152:155], v142 offset:1024
	ds_read_b128 v[156:159], v142 offset:2048
	ds_read_b128 v[160:163], v142 offset:3072
	ds_read_b128 v[164:167], v143
	ds_read_b128 v[168:171], v143 offset:1024
	ds_read_b128 v[172:175], v143 offset:2048
	ds_read_b128 v[176:179], v143 offset:3072
	s_add_u32 s48, s48, 0x100000
	s_addc_u32 s49, s49, 0
	s_mov_b32 m0, s58
	s_nop 0
	ds_read_b128 v[180:183], v151 offset:32768
	ds_read_b128 v[184:187], v151 offset:33792
	ds_read_b128 v[188:191], v151 offset:34816
	ds_read_b128 v[192:195], v151 offset:35840
	ds_read_b128 v[196:199], v151 offset:36864
	ds_read_b128 v[200:203], v151 offset:37888
	ds_read_b128 v[204:207], v151 offset:38912
	ds_read_b128 v[208:211], v151 offset:39936
	global_load_lds_dwordx4 v134, s[48:49]
	v_lshl_add_u64 v[220:221], s[48:49], 0, v[130:131]
	s_mov_b32 m0, s59
	s_nop 0
	global_load_lds_dwordx4 v[220:221], off
	s_waitcnt vmcnt(8)
	s_waitcnt lgkmcnt(0)
	s_barrier
	v_mfma_f32_16x16x32_bf16 v[124:127], v[144:147], v[180:183], v[124:127]
	v_mfma_f32_16x16x32_bf16 v[124:127], v[152:155], v[184:187], v[124:127]
	v_mfma_f32_16x16x32_bf16 v[120:123], v[160:163], v[184:187], v[120:123]
	v_mfma_f32_16x16x32_bf16 v[120:123], v[156:159], v[180:183], v[120:123]
	v_mfma_f32_16x16x32_bf16 v[104:107], v[156:159], v[188:191], v[104:107]
	v_mfma_f32_16x16x32_bf16 v[104:107], v[160:163], v[192:195], v[104:107]
	v_mfma_f32_16x16x32_bf16 v[108:111], v[152:155], v[192:195], v[108:111]
	v_mfma_f32_16x16x32_bf16 v[108:111], v[144:147], v[188:191], v[108:111]
	v_mfma_f32_16x16x32_bf16 v[92:95], v[144:147], v[196:199], v[92:95]
	v_mfma_f32_16x16x32_bf16 v[92:95], v[152:155], v[200:203], v[92:95]
	v_mfma_f32_16x16x32_bf16 v[88:91], v[160:163], v[200:203], v[88:91]
	v_mfma_f32_16x16x32_bf16 v[88:91], v[156:159], v[196:199], v[88:91]
	v_mfma_f32_16x16x32_bf16 v[72:75], v[156:159], v[204:207], v[72:75]
	v_mfma_f32_16x16x32_bf16 v[72:75], v[160:163], v[208:211], v[72:75]
	v_mfma_f32_16x16x32_bf16 v[76:79], v[152:155], v[208:211], v[76:79]
	v_mfma_f32_16x16x32_bf16 v[76:79], v[144:147], v[204:207], v[76:79]
	v_mfma_f32_16x16x32_bf16 v[116:119], v[164:167], v[180:183], v[116:119]
	v_mfma_f32_16x16x32_bf16 v[116:119], v[168:171], v[184:187], v[116:119]
	v_mfma_f32_16x16x32_bf16 v[112:115], v[176:179], v[184:187], v[112:115]
	v_mfma_f32_16x16x32_bf16 v[112:115], v[172:175], v[180:183], v[112:115]
	v_mfma_f32_16x16x32_bf16 v[96:99], v[172:175], v[188:191], v[96:99]
	v_mfma_f32_16x16x32_bf16 v[96:99], v[176:179], v[192:195], v[96:99]
	v_mfma_f32_16x16x32_bf16 v[100:103], v[168:171], v[192:195], v[100:103]
	v_mfma_f32_16x16x32_bf16 v[100:103], v[164:167], v[188:191], v[100:103]
	v_mfma_f32_16x16x32_bf16 v[84:87], v[164:167], v[196:199], v[84:87]
	v_mfma_f32_16x16x32_bf16 v[84:87], v[168:171], v[200:203], v[84:87]
	v_mfma_f32_16x16x32_bf16 v[80:83], v[176:179], v[200:203], v[80:83]
	v_mfma_f32_16x16x32_bf16 v[80:83], v[172:175], v[196:199], v[80:83]
	v_mfma_f32_16x16x32_bf16 v[64:67], v[172:175], v[204:207], v[64:67]
	v_mfma_f32_16x16x32_bf16 v[64:67], v[176:179], v[208:211], v[64:67]
	v_mfma_f32_16x16x32_bf16 v[68:71], v[168:171], v[208:211], v[68:71]
	v_mfma_f32_16x16x32_bf16 v[68:71], v[164:167], v[204:207], v[68:71]
	s_barrier
	s_mov_b32 m0, s82
	v_lshl_add_u64 v[212:213], v[212:213], 0, s[12:13]
	s_add_u32 s46, s46, 0x100080
	ds_read_b128 v[180:183], v151 offset:49152
	ds_read_b128 v[184:187], v151 offset:50176
	ds_read_b128 v[188:191], v151 offset:51200
	ds_read_b128 v[192:195], v151 offset:52224
	ds_read_b128 v[196:199], v151 offset:53248
	ds_read_b128 v[200:203], v151 offset:54272
	ds_read_b128 v[204:207], v151 offset:55296
	ds_read_b128 v[208:211], v151 offset:56320
	global_load_lds_dwordx4 v[212:213], off
	v_lshl_add_u64 v[212:213], v[214:215], 0, s[12:13]
	s_mov_b32 m0, s83
	s_addc_u32 s47, s47, 0
	global_load_lds_dwordx4 v[212:213], off
	s_nop 0
	s_mov_b32 m0, s84
	s_nop 0
	global_load_lds_dwordx4 v132, s[46:47]
	s_nop 0
	s_mov_b32 m0, s85
	s_nop 0
	global_load_lds_dwordx4 v128, s[46:47]
	v_lshl_add_u64 v[212:213], v[216:217], 0, s[12:13]
	s_mov_b32 m0, s62
	s_nop 0
	global_load_lds_dwordx4 v[212:213], off
	v_lshl_add_u64 v[212:213], v[218:219], 0, s[12:13]
	s_mov_b32 m0, s63
	s_nop 0
	global_load_lds_dwordx4 v[212:213], off
	s_waitcnt vmcnt(8)
	s_waitcnt lgkmcnt(0)
	s_barrier
	v_mfma_f32_16x16x32_bf16 v[60:63], v[144:147], v[180:183], v[60:63]
	v_mfma_f32_16x16x32_bf16 v[60:63], v[152:155], v[184:187], v[60:63]
	v_mfma_f32_16x16x32_bf16 v[56:59], v[160:163], v[184:187], v[56:59]
	v_mfma_f32_16x16x32_bf16 v[56:59], v[156:159], v[180:183], v[56:59]
	v_mfma_f32_16x16x32_bf16 v[40:43], v[156:159], v[188:191], v[40:43]
	v_mfma_f32_16x16x32_bf16 v[40:43], v[160:163], v[192:195], v[40:43]
	v_mfma_f32_16x16x32_bf16 v[44:47], v[152:155], v[192:195], v[44:47]
	v_mfma_f32_16x16x32_bf16 v[44:47], v[144:147], v[188:191], v[44:47]
	v_mfma_f32_16x16x32_bf16 v[28:31], v[144:147], v[196:199], v[28:31]
	v_mfma_f32_16x16x32_bf16 v[28:31], v[152:155], v[200:203], v[28:31]
	v_mfma_f32_16x16x32_bf16 v[24:27], v[160:163], v[200:203], v[24:27]
	v_mfma_f32_16x16x32_bf16 v[24:27], v[156:159], v[196:199], v[24:27]
	v_mfma_f32_16x16x32_bf16 v[8:11], v[156:159], v[204:207], v[8:11]
	v_mfma_f32_16x16x32_bf16 v[8:11], v[160:163], v[208:211], v[8:11]
	v_mfma_f32_16x16x32_bf16 v[12:15], v[152:155], v[208:211], v[12:15]
	v_mfma_f32_16x16x32_bf16 v[12:15], v[144:147], v[204:207], v[12:15]
	v_mfma_f32_16x16x32_bf16 v[52:55], v[164:167], v[180:183], v[52:55]
	v_mfma_f32_16x16x32_bf16 v[52:55], v[168:171], v[184:187], v[52:55]
	v_mfma_f32_16x16x32_bf16 v[48:51], v[176:179], v[184:187], v[48:51]
	v_mfma_f32_16x16x32_bf16 v[48:51], v[172:175], v[180:183], v[48:51]
	v_mfma_f32_16x16x32_bf16 v[32:35], v[172:175], v[188:191], v[32:35]
	v_mfma_f32_16x16x32_bf16 v[32:35], v[176:179], v[192:195], v[32:35]
	v_mfma_f32_16x16x32_bf16 v[36:39], v[168:171], v[192:195], v[36:39]
	v_mfma_f32_16x16x32_bf16 v[36:39], v[164:167], v[188:191], v[36:39]
	v_mfma_f32_16x16x32_bf16 v[20:23], v[164:167], v[196:199], v[20:23]
	v_mfma_f32_16x16x32_bf16 v[20:23], v[168:171], v[200:203], v[20:23]
	v_mfma_f32_16x16x32_bf16 v[16:19], v[176:179], v[200:203], v[16:19]
	v_mfma_f32_16x16x32_bf16 v[16:19], v[172:175], v[196:199], v[16:19]
	v_mfma_f32_16x16x32_bf16 v[0:3], v[172:175], v[204:207], v[0:3]
	v_mfma_f32_16x16x32_bf16 v[0:3], v[176:179], v[208:211], v[0:3]
	v_mfma_f32_16x16x32_bf16 v[4:7], v[168:171], v[208:211], v[4:7]
	v_mfma_f32_16x16x32_bf16 v[4:7], v[164:167], v[204:207], v[4:7]
	s_barrier
	s_add_i32 s88, s88, 2
	s_add_u32 s44, s44, 0x100
	s_addc_u32 s45, s45, 0
	s_add_u32 s86, s86, 0x100
	s_addc_u32 s87, s87, 0
	s_cmp_gt_u32 s88, 61
	s_cbranch_scc0 .LBB0_1343
	s_and_b64 vcc, exec, s[14:15]
	s_cbranch_vccz .LBB0_1346
	s_barrier

; #define PG8_STAGE(bufoff, gbase, voff) do { _Pragma("unroll") for (int _i = 0; _i < 2; ++_i) \
;         __builtin_amdgcn_global_load_lds((const unsigned*)((const char*)(gbase) + (voff)[_i]), (PG8_LAS unsigned*)(lds + (bufoff) + ldsw + _i * 8192), 16, 0, 0); } while (0)
; #define PG8_LDA(dst, b, h) do { _Pragma("unroll") for (int m = 0; m < 4; ++m) _Pragma("unroll") for (int k = 0; k < 2; ++k) dst[m][k] = *(const PG8_LAS bf16x8*)(lds + PG8_SA(b, h) + aoff + m * 2048 + k * 1024); } while (0)
; #define PG8_LDB(dst, b, h) do { _Pragma("unroll") for (int n = 0; n < 2; ++n) _Pragma("unroll") for (int k = 0; k < 2; ++k) dst[n][k] = *(const PG8_LAS bf16x8*)(lds + PG8_SB(b, h) + boff + n * 2048 + k * 1024); } while (0)
; #define PG8_MMA(ai, bj, At, Bt) do { __builtin_amdgcn_s_setprio(1); _Pragma("unroll") for (int m = 0; m < 4; ++m) _Pragma("unroll") for (int n = 0; n < 2; ++n) _Pragma("unroll") for (int k = 0; k < 2; ++k) \
;         acc[ai][bj][m][n] = __builtin_amdgcn_mfma_f32_16x16x32_bf16(Bt[n][k], At[m][k], acc[ai][bj][m][n], 0, 0, 0); __builtin_amdgcn_s_setprio(0); } while (0)
; #define PG8_WAIT_V(n) asm volatile("s_waitcnt vmcnt(" #n ")" ::: "memory")
; #define PG8_WAIT_L(n) asm volatile("s_waitcnt lgkmcnt(" #n ")" ::: "memory")
; #define PG8_BAR __builtin_amdgcn_s_barrier()
; template <class Epi, class Sched, bool ALIGN_EPI = false, bool SP2 = false>
; __device__ __forceinline__ void gemm_phase(PG8_LAS unsigned char* lds, const Gemm g, const Sched& S, const Epi& E, int wave_s) {
;     ...
;             const char* a1 = cA + (size_t)(t + 1) * kstep;
;             const char* a2 = last ? nA : cA + (size_t)(t + 2) * kstep; const char* b2 = last ? nB : cB + (size_t)(t + 2) * kstep;
;             const char* a3 = a2 + kstep; const char* b3 = b2 + kstep;
;             if (last && has_next) S.a_ready(nxt);
;             if constexpr (SP2) {
;             PG8_LDB(B0, 0, 0); PG8_LDB(B1, 0, 1); PG8_SCHED; PG8_LDA(At, 0, 0); PG8_STAGE(PG8_SA(1, 1), a1 + hstep, voffA);
;             PG8_WAIT_V(8); PG8_WAIT_L(0); PG8_BAR; PG8_MMA(0, 0, At, B0); PG8_MMA(0, 1, At, B1); PG8_BAR; PG8_SCHED;
;             PG8_LDA(At, 0, 1); PG8_STAGE(PG8_SB(0, 0), b2, voffB); PG8_STAGE(PG8_SB(0, 1), b2 + hstep, voffB); PG8_STAGE(PG8_SA(0, 0), a2, voffA);
;             PG8_WAIT_V(8); PG8_WAIT_L(0); PG8_BAR; PG8_MMA(1, 0, At, B0); PG8_MMA(1, 1, At, B1); PG8_BAR; PG8_SCHED;
.LBB0_1410:
	ds_read_b128 v[128:131], v211
	ds_read_b128 v[132:135], v211 offset:1024
	ds_read_b128 v[136:139], v211 offset:2048
	ds_read_b128 v[140:143], v211 offset:3072
	ds_read_b128 v[144:147], v212
	ds_read_b128 v[148:151], v212 offset:1024
	ds_read_b128 v[152:155], v212 offset:2048
	ds_read_b128 v[156:159], v212 offset:3072
	s_add_u32 s45, s50, 0xffc00080
	s_addc_u32 s52, s51, -1
	s_cmp_eq_u32 s85, s43
	s_cselect_b32 s55, s47, s52
	s_cselect_b32 s54, s46, s45
	s_cselect_b32 s53, s49, s41
	s_cselect_b32 s52, s48, s7
	s_nop 0
	s_add_i32 m0, s9, 0xc000
	ds_read_b128 v[160:163], v213
	ds_read_b128 v[164:167], v213 offset:1024
	ds_read_b128 v[168:171], v213 offset:2048
	ds_read_b128 v[172:175], v213 offset:3072
	ds_read_b128 v[176:179], v213 offset:4096
	ds_read_b128 v[180:183], v213 offset:5120
	ds_read_b128 v[196:199], v213 offset:6144
	ds_read_b128 v[200:203], v213 offset:7168
	global_load_lds_dwordx4 v192, s[50:51]
	s_nop 0
	s_add_i32 m0, s9, 0xe000
	s_nop 0
	global_load_lds_dwordx4 v194, s[50:51]
	s_waitcnt vmcnt(8)
	s_waitcnt lgkmcnt(0)
	s_barrier
	v_mfma_f32_16x16x32_bf16 v[124:127], v[128:131], v[160:163], v[124:127]
	v_mfma_f32_16x16x32_bf16 v[124:127], v[132:135], v[164:167], v[124:127]
	v_mfma_f32_16x16x32_bf16 v[120:123], v[140:143], v[164:167], v[120:123]
	v_mfma_f32_16x16x32_bf16 v[120:123], v[136:139], v[160:163], v[120:123]
	v_mfma_f32_16x16x32_bf16 v[104:107], v[136:139], v[168:171], v[104:107]
	v_mfma_f32_16x16x32_bf16 v[104:107], v[140:143], v[172:175], v[104:107]
	v_mfma_f32_16x16x32_bf16 v[108:111], v[132:135], v[172:175], v[108:111]
	v_mfma_f32_16x16x32_bf16 v[108:111], v[128:131], v[168:171], v[108:111]
	v_mfma_f32_16x16x32_bf16 v[92:95], v[128:131], v[176:179], v[92:95]
	v_mfma_f32_16x16x32_bf16 v[92:95], v[132:135], v[180:183], v[92:95]
	v_mfma_f32_16x16x32_bf16 v[88:91], v[140:143], v[180:183], v[88:91]
	v_mfma_f32_16x16x32_bf16 v[88:91], v[136:139], v[176:179], v[88:91]
	v_mfma_f32_16x16x32_bf16 v[72:75], v[136:139], v[196:199], v[72:75]
	v_mfma_f32_16x16x32_bf16 v[72:75], v[140:143], v[200:203], v[72:75]
	v_mfma_f32_16x16x32_bf16 v[76:79], v[132:135], v[200:203], v[76:79]
	v_mfma_f32_16x16x32_bf16 v[76:79], v[128:131], v[196:199], v[76:79]
	v_mfma_f32_16x16x32_bf16 v[116:119], v[144:147], v[160:163], v[116:119]
	v_mfma_f32_16x16x32_bf16 v[116:119], v[148:151], v[164:167], v[116:119]
	v_mfma_f32_16x16x32_bf16 v[112:115], v[156:159], v[164:167], v[112:115]
	v_mfma_f32_16x16x32_bf16 v[112:115], v[152:155], v[160:163], v[112:115]
	v_mfma_f32_16x16x32_bf16 v[96:99], v[152:155], v[168:171], v[96:99]
	v_mfma_f32_16x16x32_bf16 v[96:99], v[156:159], v[172:175], v[96:99]
	v_mfma_f32_16x16x32_bf16 v[100:103], v[148:151], v[172:175], v[100:103]
	v_mfma_f32_16x16x32_bf16 v[100:103], v[144:147], v[168:171], v[100:103]
	v_mfma_f32_16x16x32_bf16 v[84:87], v[144:147], v[176:179], v[84:87]
	v_mfma_f32_16x16x32_bf16 v[84:87], v[148:151], v[180:183], v[84:87]
	v_mfma_f32_16x16x32_bf16 v[80:83], v[156:159], v[180:183], v[80:83]
	v_mfma_f32_16x16x32_bf16 v[80:83], v[152:155], v[176:179], v[80:83]
	v_mfma_f32_16x16x32_bf16 v[64:67], v[152:155], v[196:199], v[64:67]
	v_mfma_f32_16x16x32_bf16 v[64:67], v[156:159], v[200:203], v[64:67]
	v_mfma_f32_16x16x32_bf16 v[68:71], v[148:151], v[200:203], v[68:71]
	v_mfma_f32_16x16x32_bf16 v[68:71], v[144:147], v[196:199], v[68:71]
	s_barrier
	s_add_i32 s45, s75, s60
	v_lshl_add_u64 v[204:205], s[52:53], 0, v[186:187]
	s_mov_b32 m0, s45
	ds_read_b128 v[160:163], v213 offset:16384
	ds_read_b128 v[164:167], v213 offset:17408
	ds_read_b128 v[168:171], v213 offset:18432
	ds_read_b128 v[172:175], v213 offset:19456
	ds_read_b128 v[176:179], v213 offset:20480
	ds_read_b128 v[180:183], v213 offset:21504
	ds_read_b128 v[196:199], v213 offset:22528
	ds_read_b128 v[200:203], v213 offset:23552
	global_load_lds_dwordx4 v[204:205], off
	s_add_i32 m0, s45, 0x2000
	s_add_u32 s86, s52, 0x400000
	v_lshl_add_u64 v[206:207], s[52:53], 0, v[190:191]
	s_addc_u32 s87, s53, 0
	s_add_i32 s45, s76, s60
	global_load_lds_dwordx4 v[206:207], off
	s_nop 0
	s_mov_b32 m0, s45
	v_lshl_add_u64 v[216:217], s[54:55], 0, v[188:189]
	global_load_lds_dwordx4 v186, s[86:87]
	s_nop 0
	s_add_i32 m0, s45, 0x2000
	s_nop 0
	global_load_lds_dwordx4 v190, s[86:87]
	v_lshl_add_u64 v[208:209], s[54:55], 0, v[184:185]
	s_mov_b32 m0, s9
	s_nop 0
	global_load_lds_dwordx4 v[208:209], off
	s_mov_b32 m0, s61
	s_nop 0
	global_load_lds_dwordx4 v[216:217], off
	s_waitcnt vmcnt(8)
	s_waitcnt lgkmcnt(0)
	s_barrier
	v_mfma_f32_16x16x32_bf16 v[60:63], v[128:131], v[160:163], v[60:63]
	v_mfma_f32_16x16x32_bf16 v[60:63], v[132:135], v[164:167], v[60:63]
	v_mfma_f32_16x16x32_bf16 v[56:59], v[140:143], v[164:167], v[56:59]
	v_mfma_f32_16x16x32_bf16 v[56:59], v[136:139], v[160:163], v[56:59]
	v_mfma_f32_16x16x32_bf16 v[40:43], v[136:139], v[168:171], v[40:43]
	v_mfma_f32_16x16x32_bf16 v[40:43], v[140:143], v[172:175], v[40:43]
	v_mfma_f32_16x16x32_bf16 v[44:47], v[132:135], v[172:175], v[44:47]
	v_mfma_f32_16x16x32_bf16 v[44:47], v[128:131], v[168:171], v[44:47]
	v_mfma_f32_16x16x32_bf16 v[28:31], v[128:131], v[176:179], v[28:31]
	v_mfma_f32_16x16x32_bf16 v[28:31], v[132:135], v[180:183], v[28:31]
	v_mfma_f32_16x16x32_bf16 v[24:27], v[140:143], v[180:183], v[24:27]
	v_mfma_f32_16x16x32_bf16 v[24:27], v[136:139], v[176:179], v[24:27]
	v_mfma_f32_16x16x32_bf16 v[8:11], v[136:139], v[196:199], v[8:11]
	v_mfma_f32_16x16x32_bf16 v[8:11], v[140:143], v[200:203], v[8:11]
	v_mfma_f32_16x16x32_bf16 v[12:15], v[132:135], v[200:203], v[12:15]
	v_mfma_f32_16x16x32_bf16 v[12:15], v[128:131], v[196:199], v[12:15]
	v_mfma_f32_16x16x32_bf16 v[52:55], v[144:147], v[160:163], v[52:55]
	v_mfma_f32_16x16x32_bf16 v[52:55], v[148:151], v[164:167], v[52:55]
	v_mfma_f32_16x16x32_bf16 v[48:51], v[156:159], v[164:167], v[48:51]
	v_mfma_f32_16x16x32_bf16 v[48:51], v[152:155], v[160:163], v[48:51]
	v_mfma_f32_16x16x32_bf16 v[32:35], v[152:155], v[168:171], v[32:35]
	v_mfma_f32_16x16x32_bf16 v[32:35], v[156:159], v[172:175], v[32:35]
	v_mfma_f32_16x16x32_bf16 v[36:39], v[148:151], v[172:175], v[36:39]
	v_mfma_f32_16x16x32_bf16 v[36:39], v[144:147], v[168:171], v[36:39]
	v_mfma_f32_16x16x32_bf16 v[20:23], v[144:147], v[176:179], v[20:23]
	v_mfma_f32_16x16x32_bf16 v[20:23], v[148:151], v[180:183], v[20:23]
	v_mfma_f32_16x16x32_bf16 v[16:19], v[156:159], v[180:183], v[16:19]
	v_mfma_f32_16x16x32_bf16 v[16:19], v[152:155], v[176:179], v[16:19]
	v_mfma_f32_16x16x32_bf16 v[0:3], v[152:155], v[196:199], v[0:3]
	v_mfma_f32_16x16x32_bf16 v[0:3], v[156:159], v[200:203], v[0:3]
	v_mfma_f32_16x16x32_bf16 v[4:7], v[148:151], v[200:203], v[4:7]
	v_mfma_f32_16x16x32_bf16 v[4:7], v[144:147], v[196:199], v[4:7]
	s_barrier
; #define PG8_LAS __attribute__((address_space(3)))
; #define PG8_STAGE(bufoff, gbase, voff) do { _Pragma("unroll") for (int _i = 0; _i < 2; ++_i) \
;         __builtin_amdgcn_global_load_lds((const unsigned*)((const char*)(gbase) + (voff)[_i]), (PG8_LAS unsigned*)(lds + (bufoff) + ldsw + _i * 8192), 16, 0, 0); } while (0)
; #define PG8_LDA(dst, b, h) do { _Pragma("unroll") for (int m = 0; m < 4; ++m) _Pragma("unroll") for (int k = 0; k < 2; ++k) dst[m][k] = *(const PG8_LAS bf16x8*)(lds + PG8_SA(b, h) + aoff + m * 2048 + k * 1024); } while (0)
; #define PG8_LDB(dst, b, h) do { _Pragma("unroll") for (int n = 0; n < 2; ++n) _Pragma("unroll") for (int k = 0; k < 2; ++k) dst[n][k] = *(const PG8_LAS bf16x8*)(lds + PG8_SB(b, h) + boff + n * 2048 + k * 1024); } while (0)
; #define PG8_WAIT_V(n) asm volatile("s_waitcnt vmcnt(" #n ")" ::: "memory")
; #define PG8_WAIT_L(n) asm volatile("s_waitcnt lgkmcnt(" #n ")" ::: "memory")
; #define PG8_BAR __builtin_amdgcn_s_barrier()
; #define PG8_SCHED __builtin_amdgcn_sched_barrier(0)
; template <class Epi, class Sched, bool ALIGN_EPI = false, bool SP2 = false>
; __device__ __forceinline__ void gemm_phase(PG8_LAS unsigned char* lds, const Gemm g, const Sched& S, const Epi& E, int wave_s) {
;     ...
;         for (int t = 0; t < nt; t += 2) {
;             const bool last = (t == nt - 2);
;             if constexpr (Epi::NEED_RS) { if (t == 0 && wid < 4) __builtin_amdgcn_global_load_lds((const unsigned*)(E.rstd + cur.pm * BM + wid * 64 + lane), (PG8_LAS unsigned*)(rsl + wid * 64), 4, 0, 0); }
;             const char* a1 = cA + (size_t)(t + 1) * kstep;
;             const char* a2 = last ? nA : cA + (size_t)(t + 2) * kstep; const char* b2 = last ? nB : cB + (size_t)(t + 2) * kstep;
;             const char* a3 = a2 + kstep; const char* b3 = b2 + kstep;
;     ...
;             PG8_LDB(B0, 1, 0); PG8_LDB(B1, 1, 1); PG8_SCHED; PG8_LDA(At, 1, 0); PG8_STAGE(PG8_SA(0, 1), a2 + hstep, voffA);
;             PG8_WAIT_V(8); PG8_WAIT_L(0); PG8_BAR; PG8_MMA(0, 0, At, B0); PG8_MMA(0, 1, At, B1); PG8_BAR; PG8_SCHED;
;             PG8_LDA(At, 1, 1); PG8_STAGE(PG8_SB(1, 0), b3, voffB); PG8_STAGE(PG8_SB(1, 1), b3 + hstep, voffB); PG8_STAGE(PG8_SA(1, 0), a3, voffA);
;             PG8_WAIT_V(8); PG8_WAIT_L(0); PG8_BAR; PG8_MMA(1, 0, At, B0); PG8_MMA(1, 1, At, B1); PG8_BAR; PG8_SCHED;
	s_add_i32 s45, 0, 0x18000
	s_add_i32 s86, 0, 0x1c000
	v_add_u32_e32 v140, s45, v210
	v_add_u32_e32 v156, s86, v210
	ds_read_b128 v[128:131], v140
	ds_read_b128 v[132:135], v140 offset:1024
	ds_read_b128 v[136:139], v140 offset:2048
	ds_read_b128 v[140:143], v140 offset:3072
	ds_read_b128 v[144:147], v156
	ds_read_b128 v[148:151], v156 offset:1024
	ds_read_b128 v[152:155], v156 offset:2048
	ds_read_b128 v[156:159], v156 offset:3072
	s_add_u32 s54, s54, 0x400000
	s_addc_u32 s55, s55, 0
	s_mov_b32 m0, s62
	s_nop 0
	ds_read_b128 v[160:163], v213 offset:32768
	ds_read_b128 v[164:167], v213 offset:33792
	ds_read_b128 v[168:171], v213 offset:34816
	ds_read_b128 v[172:175], v213 offset:35840
	ds_read_b128 v[176:179], v213 offset:36864
	ds_read_b128 v[180:183], v213 offset:37888
	ds_read_b128 v[196:199], v213 offset:38912
	ds_read_b128 v[200:203], v213 offset:39936
	global_load_lds_dwordx4 v184, s[54:55]
	v_lshl_add_u64 v[218:219], s[54:55], 0, v[188:189]
	s_mov_b32 m0, s63
	s_nop 0
	global_load_lds_dwordx4 v[218:219], off
	s_waitcnt vmcnt(8)
	s_waitcnt lgkmcnt(0)
	s_barrier
	v_mfma_f32_16x16x32_bf16 v[124:127], v[128:131], v[160:163], v[124:127]
	v_mfma_f32_16x16x32_bf16 v[124:127], v[132:135], v[164:167], v[124:127]
	v_mfma_f32_16x16x32_bf16 v[120:123], v[140:143], v[164:167], v[120:123]
	v_mfma_f32_16x16x32_bf16 v[120:123], v[136:139], v[160:163], v[120:123]
	v_mfma_f32_16x16x32_bf16 v[104:107], v[136:139], v[168:171], v[104:107]
	v_mfma_f32_16x16x32_bf16 v[104:107], v[140:143], v[172:175], v[104:107]
	v_mfma_f32_16x16x32_bf16 v[108:111], v[132:135], v[172:175], v[108:111]
	v_mfma_f32_16x16x32_bf16 v[108:111], v[128:131], v[168:171], v[108:111]
	v_mfma_f32_16x16x32_bf16 v[92:95], v[128:131], v[176:179], v[92:95]
	v_mfma_f32_16x16x32_bf16 v[92:95], v[132:135], v[180:183], v[92:95]
	v_mfma_f32_16x16x32_bf16 v[88:91], v[140:143], v[180:183], v[88:91]
	v_mfma_f32_16x16x32_bf16 v[88:91], v[136:139], v[176:179], v[88:91]
	v_mfma_f32_16x16x32_bf16 v[72:75], v[136:139], v[196:199], v[72:75]
	v_mfma_f32_16x16x32_bf16 v[72:75], v[140:143], v[200:203], v[72:75]
	v_mfma_f32_16x16x32_bf16 v[76:79], v[132:135], v[200:203], v[76:79]
	v_mfma_f32_16x16x32_bf16 v[76:79], v[128:131], v[196:199], v[76:79]
	v_mfma_f32_16x16x32_bf16 v[116:119], v[144:147], v[160:163], v[116:119]
	v_mfma_f32_16x16x32_bf16 v[116:119], v[148:151], v[164:167], v[116:119]
	v_mfma_f32_16x16x32_bf16 v[112:115], v[156:159], v[164:167], v[112:115]
	v_mfma_f32_16x16x32_bf16 v[112:115], v[152:155], v[160:163], v[112:115]
	v_mfma_f32_16x16x32_bf16 v[96:99], v[152:155], v[168:171], v[96:99]
	v_mfma_f32_16x16x32_bf16 v[96:99], v[156:159], v[172:175], v[96:99]
	v_mfma_f32_16x16x32_bf16 v[100:103], v[148:151], v[172:175], v[100:103]
	v_mfma_f32_16x16x32_bf16 v[100:103], v[144:147], v[168:171], v[100:103]
	v_mfma_f32_16x16x32_bf16 v[84:87], v[144:147], v[176:179], v[84:87]
	v_mfma_f32_16x16x32_bf16 v[84:87], v[148:151], v[180:183], v[84:87]
	v_mfma_f32_16x16x32_bf16 v[80:83], v[156:159], v[180:183], v[80:83]
	v_mfma_f32_16x16x32_bf16 v[80:83], v[152:155], v[176:179], v[80:83]
	v_mfma_f32_16x16x32_bf16 v[64:67], v[152:155], v[196:199], v[64:67]
	v_mfma_f32_16x16x32_bf16 v[64:67], v[156:159], v[200:203], v[64:67]
	v_mfma_f32_16x16x32_bf16 v[68:71], v[148:151], v[200:203], v[68:71]
	v_mfma_f32_16x16x32_bf16 v[68:71], v[144:147], v[196:199], v[68:71]
	s_barrier
	s_add_i32 s45, s45, s60
	v_lshl_add_u64 v[204:205], v[204:205], 0, s[18:19]
	s_mov_b32 m0, s45
	ds_read_b128 v[160:163], v213 offset:49152
	ds_read_b128 v[164:167], v213 offset:50176
	ds_read_b128 v[168:171], v213 offset:51200
	ds_read_b128 v[172:175], v213 offset:52224
	ds_read_b128 v[176:179], v213 offset:53248
	ds_read_b128 v[180:183], v213 offset:54272
	ds_read_b128 v[196:199], v213 offset:55296
	ds_read_b128 v[200:203], v213 offset:56320
	global_load_lds_dwordx4 v[204:205], off
	s_add_i32 m0, s45, 0x2000
	s_add_u32 s52, s52, 0x400080
	v_lshl_add_u64 v[204:205], v[206:207], 0, s[18:19]
	s_addc_u32 s53, s53, 0
	s_add_i32 s45, s86, s60
	global_load_lds_dwordx4 v[204:205], off
	s_nop 0
	s_mov_b32 m0, s45
	s_nop 0
	global_load_lds_dwordx4 v186, s[52:53]
	s_nop 0
	s_add_i32 m0, s45, 0x2000
	s_nop 0
	global_load_lds_dwordx4 v190, s[52:53]
	v_lshl_add_u64 v[204:205], v[208:209], 0, s[18:19]
	s_mov_b32 m0, s70
	s_nop 0
	global_load_lds_dwordx4 v[204:205], off
	v_lshl_add_u64 v[204:205], v[216:217], 0, s[18:19]
	s_mov_b32 m0, s71
	s_nop 0
	global_load_lds_dwordx4 v[204:205], off
	s_waitcnt vmcnt(8)
	s_waitcnt lgkmcnt(0)
	s_barrier
	v_mfma_f32_16x16x32_bf16 v[60:63], v[128:131], v[160:163], v[60:63]
	v_mfma_f32_16x16x32_bf16 v[60:63], v[132:135], v[164:167], v[60:63]
	v_mfma_f32_16x16x32_bf16 v[56:59], v[140:143], v[164:167], v[56:59]
	v_mfma_f32_16x16x32_bf16 v[56:59], v[136:139], v[160:163], v[56:59]
	v_mfma_f32_16x16x32_bf16 v[40:43], v[136:139], v[168:171], v[40:43]
	v_mfma_f32_16x16x32_bf16 v[40:43], v[140:143], v[172:175], v[40:43]
	v_mfma_f32_16x16x32_bf16 v[44:47], v[132:135], v[172:175], v[44:47]
	v_mfma_f32_16x16x32_bf16 v[44:47], v[128:131], v[168:171], v[44:47]
	v_mfma_f32_16x16x32_bf16 v[28:31], v[128:131], v[176:179], v[28:31]
	v_mfma_f32_16x16x32_bf16 v[28:31], v[132:135], v[180:183], v[28:31]
	v_mfma_f32_16x16x32_bf16 v[24:27], v[140:143], v[180:183], v[24:27]
	v_mfma_f32_16x16x32_bf16 v[24:27], v[136:139], v[176:179], v[24:27]
	v_mfma_f32_16x16x32_bf16 v[8:11], v[136:139], v[196:199], v[8:11]
	v_mfma_f32_16x16x32_bf16 v[8:11], v[140:143], v[200:203], v[8:11]
	v_mfma_f32_16x16x32_bf16 v[12:15], v[132:135], v[200:203], v[12:15]
	v_mfma_f32_16x16x32_bf16 v[12:15], v[128:131], v[196:199], v[12:15]
	v_mfma_f32_16x16x32_bf16 v[52:55], v[144:147], v[160:163], v[52:55]
	v_mfma_f32_16x16x32_bf16 v[52:55], v[148:151], v[164:167], v[52:55]
	v_mfma_f32_16x16x32_bf16 v[48:51], v[156:159], v[164:167], v[48:51]
	v_mfma_f32_16x16x32_bf16 v[48:51], v[152:155], v[160:163], v[48:51]
	v_mfma_f32_16x16x32_bf16 v[32:35], v[152:155], v[168:171], v[32:35]
	v_mfma_f32_16x16x32_bf16 v[32:35], v[156:159], v[172:175], v[32:35]
	v_mfma_f32_16x16x32_bf16 v[36:39], v[148:151], v[172:175], v[36:39]
	v_mfma_f32_16x16x32_bf16 v[36:39], v[144:147], v[168:171], v[36:39]
	v_mfma_f32_16x16x32_bf16 v[20:23], v[144:147], v[176:179], v[20:23]
	v_mfma_f32_16x16x32_bf16 v[20:23], v[148:151], v[180:183], v[20:23]
	v_mfma_f32_16x16x32_bf16 v[16:19], v[156:159], v[180:183], v[16:19]
	v_mfma_f32_16x16x32_bf16 v[16:19], v[152:155], v[176:179], v[16:19]
	v_mfma_f32_16x16x32_bf16 v[0:3], v[152:155], v[196:199], v[0:3]
	v_mfma_f32_16x16x32_bf16 v[0:3], v[156:159], v[200:203], v[0:3]
	v_mfma_f32_16x16x32_bf16 v[4:7], v[148:151], v[200:203], v[4:7]
	v_mfma_f32_16x16x32_bf16 v[4:7], v[144:147], v[196:199], v[4:7]
	s_barrier
	s_add_i32 s45, s43, 2
	s_add_u32 s50, s50, 0x100
	s_addc_u32 s51, s51, 0
	s_add_u32 s7, s7, 0x100
	s_addc_u32 s41, s41, 0
	s_cmp_ge_i32 s43, s85
	s_mov_b32 s43, s45
	s_cbranch_scc0 .LBB0_1410
	s_and_b64 vcc, exec, s[20:21]
	s_cbranch_vccz .LBB0_1413
	s_barrier
